# all three RMSNorm latent loops hand-written with next-tile LDS-DMA prefetch
# speedup vs baseline: 1.0021x; 1.0021x over previous
.LBB0_123:
	v_mbcnt_lo_u32_b32 v112, -1, 0
	v_mbcnt_hi_u32_b32 v112, -1, v112
	v_lshl_add_u32 v93, s3, 6, v112
	v_lshlrev_b32_e32 v93, 4, v93
	v_add_u32_e32 v122, 0x10000, v93
	v_and_b32_e32 v112, 15, v112
	v_lshlrev_b32_e32 v92, 2, v112
	v_add_u32_e32 v92, 0x20100, v92
	s_lshl_b32 s17, s3, 6
	s_add_u32 s17, s17, 0x20100
	v_mov_b32_e32 v91, s17
	s_mov_b32 s12, 0x2000
	s_mov_b32 s13, 0
	s_ashr_i32 s11, s10, 31
	s_lshl_b64 s[0:1], s[10:11], 13
	s_lshl_b32 s15, s3, 10
	s_mov_b32 m0, s15
	v_lshl_add_u64 v[110:111], v[82:83], 0, s[0:1]
	global_load_lds_dwordx4 v[110:111], off
	s_add_u32 s0, s0, 0x2000
	s_addc_u32 s1, s1, 0
	s_add_u32 s15, s15, 0x2000
	s_mov_b32 m0, s15
	v_lshl_add_u64 v[110:111], v[82:83], 0, s[0:1]
	global_load_lds_dwordx4 v[110:111], off
	s_add_u32 s0, s0, 0x2000
	s_addc_u32 s1, s1, 0
	s_add_u32 s15, s15, 0x2000
	s_mov_b32 m0, s15
	v_lshl_add_u64 v[110:111], v[82:83], 0, s[0:1]
	global_load_lds_dwordx4 v[110:111], off
	s_add_u32 s0, s0, 0x2000
	s_addc_u32 s1, s1, 0
	s_add_u32 s15, s15, 0x2000
	s_mov_b32 m0, s15
	v_lshl_add_u64 v[110:111], v[82:83], 0, s[0:1]
	global_load_lds_dwordx4 v[110:111], off
	s_add_u32 s0, s0, 0x2000
	s_addc_u32 s1, s1, 0
	s_add_u32 s15, s15, 0x2000
	s_mov_b32 m0, s15
	v_lshl_add_u64 v[110:111], v[82:83], 0, s[0:1]
	global_load_lds_dwordx4 v[110:111], off
	s_add_u32 s0, s0, 0x2000
	s_addc_u32 s1, s1, 0
	s_add_u32 s15, s15, 0x2000
	s_mov_b32 m0, s15
	v_lshl_add_u64 v[110:111], v[82:83], 0, s[0:1]
	global_load_lds_dwordx4 v[110:111], off
	s_add_u32 s0, s0, 0x2000
	s_addc_u32 s1, s1, 0
	s_add_u32 s15, s15, 0x2000
	s_mov_b32 m0, s15
	v_lshl_add_u64 v[110:111], v[82:83], 0, s[0:1]
	global_load_lds_dwordx4 v[110:111], off
	s_add_u32 s0, s0, 0x2000
	s_addc_u32 s1, s1, 0
	s_add_u32 s15, s15, 0x2000
	s_mov_b32 m0, s15
	v_lshl_add_u64 v[110:111], v[82:83], 0, s[0:1]
	global_load_lds_dwordx4 v[110:111], off
	s_add_u32 s0, s0, 0x2000
	s_addc_u32 s1, s1, 0
	s_add_u32 s15, s15, 0x2000
	s_mov_b32 m0, s15
	v_lshl_add_u64 v[110:111], v[82:83], 0, s[0:1]
	global_load_lds_dwordx4 v[110:111], off
	s_add_u32 s0, s0, 0x2000
	s_addc_u32 s1, s1, 0
	s_add_u32 s15, s15, 0x2000
	s_mov_b32 m0, s15
	v_lshl_add_u64 v[110:111], v[82:83], 0, s[0:1]
	global_load_lds_dwordx4 v[110:111], off
	s_add_u32 s0, s0, 0x2000
	s_addc_u32 s1, s1, 0
	s_add_u32 s15, s15, 0x2000
	s_mov_b32 m0, s15
	v_lshl_add_u64 v[110:111], v[82:83], 0, s[0:1]
	global_load_lds_dwordx4 v[110:111], off
	s_add_u32 s0, s0, 0x2000
	s_addc_u32 s1, s1, 0
	s_add_u32 s15, s15, 0x2000
	s_mov_b32 m0, s15
	v_lshl_add_u64 v[110:111], v[82:83], 0, s[0:1]
	global_load_lds_dwordx4 v[110:111], off
	s_add_u32 s0, s0, 0x2000
	s_addc_u32 s1, s1, 0
	s_add_u32 s15, s15, 0x2000
	s_mov_b32 m0, s15
	v_lshl_add_u64 v[110:111], v[82:83], 0, s[0:1]
	global_load_lds_dwordx4 v[110:111], off
	s_add_u32 s0, s0, 0x2000
	s_addc_u32 s1, s1, 0
	s_add_u32 s15, s15, 0x2000
	s_mov_b32 m0, s15
	v_lshl_add_u64 v[110:111], v[82:83], 0, s[0:1]
	global_load_lds_dwordx4 v[110:111], off
	s_add_u32 s0, s0, 0x2000
	s_addc_u32 s1, s1, 0
	s_add_u32 s15, s15, 0x2000
	s_mov_b32 m0, s15
	v_lshl_add_u64 v[110:111], v[82:83], 0, s[0:1]
	global_load_lds_dwordx4 v[110:111], off
	s_add_u32 s0, s0, 0x2000
	s_addc_u32 s1, s1, 0
	s_add_u32 s15, s15, 0x2000
	s_mov_b32 m0, s15
	v_lshl_add_u64 v[110:111], v[82:83], 0, s[0:1]
	global_load_lds_dwordx4 v[110:111], off
	s_waitcnt vmcnt(0)
.Lnm_n1_loop:
	s_waitcnt vmcnt(16)
	ds_read_b128 v[4:7], v93
	ds_read_b128 v[8:11], v93 offset:8192
	ds_read_b128 v[12:15], v93 offset:16384
	ds_read_b128 v[16:19], v93 offset:24576
	ds_read_b128 v[20:23], v93 offset:32768
	ds_read_b128 v[24:27], v93 offset:40960
	ds_read_b128 v[28:31], v93 offset:49152
	ds_read_b128 v[32:35], v93 offset:57344
	ds_read_b128 v[36:39], v122
	ds_read_b128 v[40:43], v122 offset:8192
	ds_read_b128 v[44:47], v122 offset:16384
	ds_read_b128 v[48:51], v122 offset:24576
	ds_read_b128 v[52:55], v122 offset:32768
	ds_read_b128 v[56:59], v122 offset:40960
	ds_read_b128 v[60:63], v122 offset:49152
	ds_read_b128 v[64:67], v122 offset:57344
	s_ashr_i32 s0, s22, 8
	v_mad_i64_i32 v[110:111], s[0:1], s0, v178, v[80:81]
	v_lshl_add_u64 v[112:113], v[110:111], 0, s[12:13]
	global_load_dwordx4 v[118:121], v[112:113], off
	s_mov_b32 s0, 0x0
	s_mov_b32 s1, 0
	v_lshl_add_u64 v[112:113], v[110:111], 0, s[0:1]
	global_load_dwordx4 v[250:253], v[112:113], off
	s_waitcnt lgkmcnt(0)
	s_add_i32 s14, s22, s34
	s_add_i32 s18, s10, s88
	s_cmpk_gt_i32 s14, 0x3ff
	s_cselect_b32 s18, s10, s18
	s_ashr_i32 s19, s18, 31
	s_lshl_b64 s[0:1], s[18:19], 13
	s_lshl_b32 s15, s3, 10
	s_mov_b32 m0, s15
	v_lshl_add_u64 v[110:111], v[82:83], 0, s[0:1]
	global_load_lds_dwordx4 v[110:111], off
	s_add_u32 s0, s0, 0x2000
	s_addc_u32 s1, s1, 0
	s_add_u32 s15, s15, 0x2000
	s_mov_b32 m0, s15
	v_lshl_add_u64 v[110:111], v[82:83], 0, s[0:1]
	global_load_lds_dwordx4 v[110:111], off
	s_add_u32 s0, s0, 0x2000
	s_addc_u32 s1, s1, 0
	s_add_u32 s15, s15, 0x2000
	s_mov_b32 m0, s15
	v_lshl_add_u64 v[110:111], v[82:83], 0, s[0:1]
	global_load_lds_dwordx4 v[110:111], off
	s_add_u32 s0, s0, 0x2000
	s_addc_u32 s1, s1, 0
	s_add_u32 s15, s15, 0x2000
	s_mov_b32 m0, s15
	v_lshl_add_u64 v[110:111], v[82:83], 0, s[0:1]
	global_load_lds_dwordx4 v[110:111], off
	s_add_u32 s0, s0, 0x2000
	s_addc_u32 s1, s1, 0
	s_add_u32 s15, s15, 0x2000
	s_mov_b32 m0, s15
	v_lshl_add_u64 v[110:111], v[82:83], 0, s[0:1]
	global_load_lds_dwordx4 v[110:111], off
	s_add_u32 s0, s0, 0x2000
	s_addc_u32 s1, s1, 0
	s_add_u32 s15, s15, 0x2000
	s_mov_b32 m0, s15
	v_lshl_add_u64 v[110:111], v[82:83], 0, s[0:1]
	global_load_lds_dwordx4 v[110:111], off
	s_add_u32 s0, s0, 0x2000
	s_addc_u32 s1, s1, 0
	s_add_u32 s15, s15, 0x2000
	s_mov_b32 m0, s15
	v_lshl_add_u64 v[110:111], v[82:83], 0, s[0:1]
	global_load_lds_dwordx4 v[110:111], off
	s_add_u32 s0, s0, 0x2000
	s_addc_u32 s1, s1, 0
	s_add_u32 s15, s15, 0x2000
	s_mov_b32 m0, s15
	v_lshl_add_u64 v[110:111], v[82:83], 0, s[0:1]
	global_load_lds_dwordx4 v[110:111], off
	s_add_u32 s0, s0, 0x2000
	s_addc_u32 s1, s1, 0
	s_add_u32 s15, s15, 0x2000
	s_mov_b32 m0, s15
	v_lshl_add_u64 v[110:111], v[82:83], 0, s[0:1]
	global_load_lds_dwordx4 v[110:111], off
	s_add_u32 s0, s0, 0x2000
	s_addc_u32 s1, s1, 0
	s_add_u32 s15, s15, 0x2000
	s_mov_b32 m0, s15
	v_lshl_add_u64 v[110:111], v[82:83], 0, s[0:1]
	global_load_lds_dwordx4 v[110:111], off
	s_add_u32 s0, s0, 0x2000
	s_addc_u32 s1, s1, 0
	s_add_u32 s15, s15, 0x2000
	s_mov_b32 m0, s15
	v_lshl_add_u64 v[110:111], v[82:83], 0, s[0:1]
	global_load_lds_dwordx4 v[110:111], off
	s_add_u32 s0, s0, 0x2000
	s_addc_u32 s1, s1, 0
	s_add_u32 s15, s15, 0x2000
	s_mov_b32 m0, s15
	v_lshl_add_u64 v[110:111], v[82:83], 0, s[0:1]
	global_load_lds_dwordx4 v[110:111], off
	s_add_u32 s0, s0, 0x2000
	s_addc_u32 s1, s1, 0
	s_add_u32 s15, s15, 0x2000
	s_mov_b32 m0, s15
	v_lshl_add_u64 v[110:111], v[82:83], 0, s[0:1]
	global_load_lds_dwordx4 v[110:111], off
	s_add_u32 s0, s0, 0x2000
	s_addc_u32 s1, s1, 0
	s_add_u32 s15, s15, 0x2000
	s_mov_b32 m0, s15
	v_lshl_add_u64 v[110:111], v[82:83], 0, s[0:1]
	global_load_lds_dwordx4 v[110:111], off
	s_add_u32 s0, s0, 0x2000
	s_addc_u32 s1, s1, 0
	s_add_u32 s15, s15, 0x2000
	s_mov_b32 m0, s15
	v_lshl_add_u64 v[110:111], v[82:83], 0, s[0:1]
	global_load_lds_dwordx4 v[110:111], off
	s_add_u32 s0, s0, 0x2000
	s_addc_u32 s1, s1, 0
	s_add_u32 s15, s15, 0x2000
	s_mov_b32 m0, s15
	v_lshl_add_u64 v[110:111], v[82:83], 0, s[0:1]
	global_load_lds_dwordx4 v[110:111], off
	v_mul_f32_e32 v68, v5, v5
	v_mul_f32_e32 v102, v7, v7
	v_fmac_f32_e32 v68, v4, v4
	v_fmac_f32_e32 v102, v6, v6
	v_add_f32_e32 v68, v68, v102
	v_mul_f32_e32 v69, v9, v9
	v_mul_f32_e32 v103, v11, v11
	v_fmac_f32_e32 v69, v8, v8
	v_fmac_f32_e32 v103, v10, v10
	v_add_f32_e32 v69, v69, v103
	v_mul_f32_e32 v70, v13, v13
	v_mul_f32_e32 v104, v15, v15
	v_fmac_f32_e32 v70, v12, v12
	v_fmac_f32_e32 v104, v14, v14
	v_add_f32_e32 v70, v70, v104
	v_mul_f32_e32 v71, v17, v17
	v_mul_f32_e32 v105, v19, v19
	v_fmac_f32_e32 v71, v16, v16
	v_fmac_f32_e32 v105, v18, v18
	v_add_f32_e32 v71, v71, v105
	v_mul_f32_e32 v72, v21, v21
	v_mul_f32_e32 v106, v23, v23
	v_fmac_f32_e32 v72, v20, v20
	v_fmac_f32_e32 v106, v22, v22
	v_add_f32_e32 v72, v72, v106
	v_mul_f32_e32 v73, v25, v25
	v_mul_f32_e32 v107, v27, v27
	v_fmac_f32_e32 v73, v24, v24
	v_fmac_f32_e32 v107, v26, v26
	v_add_f32_e32 v73, v73, v107
	v_mul_f32_e32 v74, v29, v29
	v_mul_f32_e32 v108, v31, v31
	v_fmac_f32_e32 v74, v28, v28
	v_fmac_f32_e32 v108, v30, v30
	v_add_f32_e32 v74, v74, v108
	v_mul_f32_e32 v75, v33, v33
	v_mul_f32_e32 v109, v35, v35
	v_fmac_f32_e32 v75, v32, v32
	v_fmac_f32_e32 v109, v34, v34
	v_add_f32_e32 v75, v75, v109
	v_mul_f32_e32 v94, v37, v37
	v_mul_f32_e32 v110, v39, v39
	v_fmac_f32_e32 v94, v36, v36
	v_fmac_f32_e32 v110, v38, v38
	v_add_f32_e32 v94, v94, v110
	v_mul_f32_e32 v95, v41, v41
	v_mul_f32_e32 v111, v43, v43
	v_fmac_f32_e32 v95, v40, v40
	v_fmac_f32_e32 v111, v42, v42
	v_add_f32_e32 v95, v95, v111
	v_mul_f32_e32 v96, v45, v45
	v_mul_f32_e32 v112, v47, v47
	v_fmac_f32_e32 v96, v44, v44
	v_fmac_f32_e32 v112, v46, v46
	v_add_f32_e32 v96, v96, v112
	v_mul_f32_e32 v97, v49, v49
	v_mul_f32_e32 v113, v51, v51
	v_fmac_f32_e32 v97, v48, v48
	v_fmac_f32_e32 v113, v50, v50
	v_add_f32_e32 v97, v97, v113
	v_mul_f32_e32 v98, v53, v53
	v_mul_f32_e32 v114, v55, v55
	v_fmac_f32_e32 v98, v52, v52
	v_fmac_f32_e32 v114, v54, v54
	v_add_f32_e32 v98, v98, v114
	v_mul_f32_e32 v99, v57, v57
	v_mul_f32_e32 v115, v59, v59
	v_fmac_f32_e32 v99, v56, v56
	v_fmac_f32_e32 v115, v58, v58
	v_add_f32_e32 v99, v99, v115
	v_mul_f32_e32 v100, v61, v61
	v_mul_f32_e32 v116, v63, v63
	v_fmac_f32_e32 v100, v60, v60
	v_fmac_f32_e32 v116, v62, v62
	v_add_f32_e32 v100, v100, v116
	v_mul_f32_e32 v101, v65, v65
	v_mul_f32_e32 v117, v67, v67
	v_fmac_f32_e32 v101, v64, v64
	v_fmac_f32_e32 v117, v66, v66
	v_add_f32_e32 v101, v101, v117
	ds_bpermute_b32 v102, v85, v68
	ds_bpermute_b32 v103, v85, v69
	ds_bpermute_b32 v104, v85, v70
	ds_bpermute_b32 v105, v85, v71
	ds_bpermute_b32 v106, v85, v72
	ds_bpermute_b32 v107, v85, v73
	ds_bpermute_b32 v108, v85, v74
	ds_bpermute_b32 v109, v85, v75
	ds_bpermute_b32 v110, v85, v94
	ds_bpermute_b32 v111, v85, v95
	ds_bpermute_b32 v112, v85, v96
	ds_bpermute_b32 v113, v85, v97
	ds_bpermute_b32 v114, v85, v98
	ds_bpermute_b32 v115, v85, v99
	ds_bpermute_b32 v116, v85, v100
	ds_bpermute_b32 v117, v85, v101
	s_waitcnt lgkmcnt(15)
	v_add_f32_e32 v68, v68, v102
	s_waitcnt lgkmcnt(14)
	v_add_f32_e32 v69, v69, v103
	s_waitcnt lgkmcnt(13)
	v_add_f32_e32 v70, v70, v104
	s_waitcnt lgkmcnt(12)
	v_add_f32_e32 v71, v71, v105
	s_waitcnt lgkmcnt(11)
	v_add_f32_e32 v72, v72, v106
	s_waitcnt lgkmcnt(10)
	v_add_f32_e32 v73, v73, v107
	s_waitcnt lgkmcnt(9)
	v_add_f32_e32 v74, v74, v108
	s_waitcnt lgkmcnt(8)
	v_add_f32_e32 v75, v75, v109
	s_waitcnt lgkmcnt(7)
	v_add_f32_e32 v94, v94, v110
	s_waitcnt lgkmcnt(6)
	v_add_f32_e32 v95, v95, v111
	s_waitcnt lgkmcnt(5)
	v_add_f32_e32 v96, v96, v112
	s_waitcnt lgkmcnt(4)
	v_add_f32_e32 v97, v97, v113
	s_waitcnt lgkmcnt(3)
	v_add_f32_e32 v98, v98, v114
	s_waitcnt lgkmcnt(2)
	v_add_f32_e32 v99, v99, v115
	s_waitcnt lgkmcnt(1)
	v_add_f32_e32 v100, v100, v116
	s_waitcnt lgkmcnt(0)
	v_add_f32_e32 v101, v101, v117
	ds_bpermute_b32 v102, v86, v68
	ds_bpermute_b32 v103, v86, v69
	ds_bpermute_b32 v104, v86, v70
	ds_bpermute_b32 v105, v86, v71
	ds_bpermute_b32 v106, v86, v72
	ds_bpermute_b32 v107, v86, v73
	ds_bpermute_b32 v108, v86, v74
	ds_bpermute_b32 v109, v86, v75
	ds_bpermute_b32 v110, v86, v94
	ds_bpermute_b32 v111, v86, v95
	ds_bpermute_b32 v112, v86, v96
	ds_bpermute_b32 v113, v86, v97
	ds_bpermute_b32 v114, v86, v98
	ds_bpermute_b32 v115, v86, v99
	ds_bpermute_b32 v116, v86, v100
	ds_bpermute_b32 v117, v86, v101
	s_waitcnt lgkmcnt(15)
	v_add_f32_e32 v68, v68, v102
	s_waitcnt lgkmcnt(14)
	v_add_f32_e32 v69, v69, v103
	s_waitcnt lgkmcnt(13)
	v_add_f32_e32 v70, v70, v104
	s_waitcnt lgkmcnt(12)
	v_add_f32_e32 v71, v71, v105
	s_waitcnt lgkmcnt(11)
	v_add_f32_e32 v72, v72, v106
	s_waitcnt lgkmcnt(10)
	v_add_f32_e32 v73, v73, v107
	s_waitcnt lgkmcnt(9)
	v_add_f32_e32 v74, v74, v108
	s_waitcnt lgkmcnt(8)
	v_add_f32_e32 v75, v75, v109
	s_waitcnt lgkmcnt(7)
	v_add_f32_e32 v94, v94, v110
	s_waitcnt lgkmcnt(6)
	v_add_f32_e32 v95, v95, v111
	s_waitcnt lgkmcnt(5)
	v_add_f32_e32 v96, v96, v112
	s_waitcnt lgkmcnt(4)
	v_add_f32_e32 v97, v97, v113
	s_waitcnt lgkmcnt(3)
	v_add_f32_e32 v98, v98, v114
	s_waitcnt lgkmcnt(2)
	v_add_f32_e32 v99, v99, v115
	s_waitcnt lgkmcnt(1)
	v_add_f32_e32 v100, v100, v116
	s_waitcnt lgkmcnt(0)
	v_add_f32_e32 v101, v101, v117
	ds_bpermute_b32 v102, v87, v68
	ds_bpermute_b32 v103, v87, v69
	ds_bpermute_b32 v104, v87, v70
	ds_bpermute_b32 v105, v87, v71
	ds_bpermute_b32 v106, v87, v72
	ds_bpermute_b32 v107, v87, v73
	ds_bpermute_b32 v108, v87, v74
	ds_bpermute_b32 v109, v87, v75
	ds_bpermute_b32 v110, v87, v94
	ds_bpermute_b32 v111, v87, v95
	ds_bpermute_b32 v112, v87, v96
	ds_bpermute_b32 v113, v87, v97
	ds_bpermute_b32 v114, v87, v98
	ds_bpermute_b32 v115, v87, v99
	ds_bpermute_b32 v116, v87, v100
	ds_bpermute_b32 v117, v87, v101
	s_waitcnt lgkmcnt(15)
	v_add_f32_e32 v68, v68, v102
	s_waitcnt lgkmcnt(14)
	v_add_f32_e32 v69, v69, v103
	s_waitcnt lgkmcnt(13)
	v_add_f32_e32 v70, v70, v104
	s_waitcnt lgkmcnt(12)
	v_add_f32_e32 v71, v71, v105
	s_waitcnt lgkmcnt(11)
	v_add_f32_e32 v72, v72, v106
	s_waitcnt lgkmcnt(10)
	v_add_f32_e32 v73, v73, v107
	s_waitcnt lgkmcnt(9)
	v_add_f32_e32 v74, v74, v108
	s_waitcnt lgkmcnt(8)
	v_add_f32_e32 v75, v75, v109
	s_waitcnt lgkmcnt(7)
	v_add_f32_e32 v94, v94, v110
	s_waitcnt lgkmcnt(6)
	v_add_f32_e32 v95, v95, v111
	s_waitcnt lgkmcnt(5)
	v_add_f32_e32 v96, v96, v112
	s_waitcnt lgkmcnt(4)
	v_add_f32_e32 v97, v97, v113
	s_waitcnt lgkmcnt(3)
	v_add_f32_e32 v98, v98, v114
	s_waitcnt lgkmcnt(2)
	v_add_f32_e32 v99, v99, v115
	s_waitcnt lgkmcnt(1)
	v_add_f32_e32 v100, v100, v116
	s_waitcnt lgkmcnt(0)
	v_add_f32_e32 v101, v101, v117
	ds_bpermute_b32 v102, v88, v68
	ds_bpermute_b32 v103, v88, v69
	ds_bpermute_b32 v104, v88, v70
	ds_bpermute_b32 v105, v88, v71
	ds_bpermute_b32 v106, v88, v72
	ds_bpermute_b32 v107, v88, v73
	ds_bpermute_b32 v108, v88, v74
	ds_bpermute_b32 v109, v88, v75
	ds_bpermute_b32 v110, v88, v94
	ds_bpermute_b32 v111, v88, v95
	ds_bpermute_b32 v112, v88, v96
	ds_bpermute_b32 v113, v88, v97
	ds_bpermute_b32 v114, v88, v98
	ds_bpermute_b32 v115, v88, v99
	ds_bpermute_b32 v116, v88, v100
	ds_bpermute_b32 v117, v88, v101
	s_waitcnt lgkmcnt(15)
	v_add_f32_e32 v68, v68, v102
	s_waitcnt lgkmcnt(14)
	v_add_f32_e32 v69, v69, v103
	s_waitcnt lgkmcnt(13)
	v_add_f32_e32 v70, v70, v104
	s_waitcnt lgkmcnt(12)
	v_add_f32_e32 v71, v71, v105
	s_waitcnt lgkmcnt(11)
	v_add_f32_e32 v72, v72, v106
	s_waitcnt lgkmcnt(10)
	v_add_f32_e32 v73, v73, v107
	s_waitcnt lgkmcnt(9)
	v_add_f32_e32 v74, v74, v108
	s_waitcnt lgkmcnt(8)
	v_add_f32_e32 v75, v75, v109
	s_waitcnt lgkmcnt(7)
	v_add_f32_e32 v94, v94, v110
	s_waitcnt lgkmcnt(6)
	v_add_f32_e32 v95, v95, v111
	s_waitcnt lgkmcnt(5)
	v_add_f32_e32 v96, v96, v112
	s_waitcnt lgkmcnt(4)
	v_add_f32_e32 v97, v97, v113
	s_waitcnt lgkmcnt(3)
	v_add_f32_e32 v98, v98, v114
	s_waitcnt lgkmcnt(2)
	v_add_f32_e32 v99, v99, v115
	s_waitcnt lgkmcnt(1)
	v_add_f32_e32 v100, v100, v116
	s_waitcnt lgkmcnt(0)
	v_add_f32_e32 v101, v101, v117
	ds_bpermute_b32 v102, v89, v68
	ds_bpermute_b32 v103, v89, v69
	ds_bpermute_b32 v104, v89, v70
	ds_bpermute_b32 v105, v89, v71
	ds_bpermute_b32 v106, v89, v72
	ds_bpermute_b32 v107, v89, v73
	ds_bpermute_b32 v108, v89, v74
	ds_bpermute_b32 v109, v89, v75
	ds_bpermute_b32 v110, v89, v94
	ds_bpermute_b32 v111, v89, v95
	ds_bpermute_b32 v112, v89, v96
	ds_bpermute_b32 v113, v89, v97
	ds_bpermute_b32 v114, v89, v98
	ds_bpermute_b32 v115, v89, v99
	ds_bpermute_b32 v116, v89, v100
	ds_bpermute_b32 v117, v89, v101
	s_waitcnt lgkmcnt(15)
	v_add_f32_e32 v68, v68, v102
	s_waitcnt lgkmcnt(14)
	v_add_f32_e32 v69, v69, v103
	s_waitcnt lgkmcnt(13)
	v_add_f32_e32 v70, v70, v104
	s_waitcnt lgkmcnt(12)
	v_add_f32_e32 v71, v71, v105
	s_waitcnt lgkmcnt(11)
	v_add_f32_e32 v72, v72, v106
	s_waitcnt lgkmcnt(10)
	v_add_f32_e32 v73, v73, v107
	s_waitcnt lgkmcnt(9)
	v_add_f32_e32 v74, v74, v108
	s_waitcnt lgkmcnt(8)
	v_add_f32_e32 v75, v75, v109
	s_waitcnt lgkmcnt(7)
	v_add_f32_e32 v94, v94, v110
	s_waitcnt lgkmcnt(6)
	v_add_f32_e32 v95, v95, v111
	s_waitcnt lgkmcnt(5)
	v_add_f32_e32 v96, v96, v112
	s_waitcnt lgkmcnt(4)
	v_add_f32_e32 v97, v97, v113
	s_waitcnt lgkmcnt(3)
	v_add_f32_e32 v98, v98, v114
	s_waitcnt lgkmcnt(2)
	v_add_f32_e32 v99, v99, v115
	s_waitcnt lgkmcnt(1)
	v_add_f32_e32 v100, v100, v116
	s_waitcnt lgkmcnt(0)
	v_add_f32_e32 v101, v101, v117
	ds_bpermute_b32 v102, v90, v68
	ds_bpermute_b32 v103, v90, v69
	ds_bpermute_b32 v104, v90, v70
	ds_bpermute_b32 v105, v90, v71
	ds_bpermute_b32 v106, v90, v72
	ds_bpermute_b32 v107, v90, v73
	ds_bpermute_b32 v108, v90, v74
	ds_bpermute_b32 v109, v90, v75
	ds_bpermute_b32 v110, v90, v94
	ds_bpermute_b32 v111, v90, v95
	ds_bpermute_b32 v112, v90, v96
	ds_bpermute_b32 v113, v90, v97
	ds_bpermute_b32 v114, v90, v98
	ds_bpermute_b32 v115, v90, v99
	ds_bpermute_b32 v116, v90, v100
	ds_bpermute_b32 v117, v90, v101
	s_waitcnt lgkmcnt(15)
	v_add_f32_e32 v68, v68, v102
	s_waitcnt lgkmcnt(14)
	v_add_f32_e32 v69, v69, v103
	s_waitcnt lgkmcnt(13)
	v_add_f32_e32 v70, v70, v104
	s_waitcnt lgkmcnt(12)
	v_add_f32_e32 v71, v71, v105
	s_waitcnt lgkmcnt(11)
	v_add_f32_e32 v72, v72, v106
	s_waitcnt lgkmcnt(10)
	v_add_f32_e32 v73, v73, v107
	s_waitcnt lgkmcnt(9)
	v_add_f32_e32 v74, v74, v108
	s_waitcnt lgkmcnt(8)
	v_add_f32_e32 v75, v75, v109
	s_waitcnt lgkmcnt(7)
	v_add_f32_e32 v94, v94, v110
	s_waitcnt lgkmcnt(6)
	v_add_f32_e32 v95, v95, v111
	s_waitcnt lgkmcnt(5)
	v_add_f32_e32 v96, v96, v112
	s_waitcnt lgkmcnt(4)
	v_add_f32_e32 v97, v97, v113
	s_waitcnt lgkmcnt(3)
	v_add_f32_e32 v98, v98, v114
	s_waitcnt lgkmcnt(2)
	v_add_f32_e32 v99, v99, v115
	s_waitcnt lgkmcnt(1)
	v_add_f32_e32 v100, v100, v116
	s_waitcnt lgkmcnt(0)
	v_add_f32_e32 v101, v101, v117
	s_mov_b64 exec, 1
	ds_write_b128 v91, v[68:71]
	ds_write_b128 v91, v[72:75] offset:16
	ds_write_b128 v91, v[94:97] offset:32
	ds_write_b128 v91, v[98:101] offset:48
	s_mov_b64 exec, -1
	s_waitcnt lgkmcnt(0)
	s_barrier
	ds_read_b32 v102, v92
	ds_read_b32 v103, v92 offset:64
	ds_read_b32 v104, v92 offset:128
	ds_read_b32 v105, v92 offset:192
	ds_read_b32 v106, v92 offset:256
	ds_read_b32 v107, v92 offset:320
	ds_read_b32 v108, v92 offset:384
	ds_read_b32 v109, v92 offset:448
	s_waitcnt lgkmcnt(0)
	v_add_f32_e32 v102, v102, v103
	v_add_f32_e32 v104, v104, v105
	v_add_f32_e32 v106, v106, v107
	v_add_f32_e32 v108, v108, v109
	v_add_f32_e32 v102, v102, v104
	v_add_f32_e32 v106, v106, v108
	v_add_f32_e32 v102, v102, v106
	v_fmamk_f32 v102, v102, 0x3a000000, v173
	v_cmp_gt_f32_e32 vcc, s33, v102
	v_mul_f32_e32 v116, 0x4f800000, v102
	s_nop 1
	v_cndmask_b32_e32 v102, v102, v116, vcc
	v_sqrt_f32_e32 v116, v102
	s_nop 1
	v_add_u32_e32 v111, -1, v116
	v_fma_f32 v112, -v111, v116, v102
	v_cmp_ge_f32_e64 s[14:15], 0, v112
	v_add_u32_e32 v112, 1, v116
	s_nop 1
	v_cndmask_b32_e64 v111, v116, v111, s[14:15]
	v_fma_f32 v116, -v112, v116, v102
	v_cmp_lt_f32_e64 s[14:15], 0, v116
	s_nop 1
	v_cndmask_b32_e64 v116, v111, v112, s[14:15]
	v_mul_f32_e32 v111, 0x37800000, v116
	v_cndmask_b32_e32 v116, v116, v111, vcc
	v_cmp_class_f32_e32 vcc, v102, v174
	s_nop 1
	v_cndmask_b32_e32 v102, v116, v102, vcc
	v_div_scale_f32 v116, s[16:17], v102, v102, 1.0
	v_rcp_f32_e32 v111, v116
	s_nop 0
	v_fma_f32 v112, -v116, v111, 1.0
	v_fmac_f32_e32 v111, v112, v111
	v_div_scale_f32 v112, vcc, 1.0, v102, 1.0
	v_mul_f32_e32 v113, v112, v111
	v_fma_f32 v114, -v116, v113, v112
	v_fmac_f32_e32 v113, v114, v111
	v_fma_f32 v116, -v116, v113, v112
	v_div_fmas_f32 v116, v116, v111, v113
	v_div_fixup_f32 v116, v116, v102, 1.0
	s_waitcnt vmcnt(16)
	v_pk_add_f32 v[118:119], v[118:119], 1.0 op_sel_hi:[1,0]
	v_pk_add_f32 v[120:121], v[120:121], 1.0 op_sel_hi:[1,0]
	v_pk_mul_f32 v[104:105], v[0:1], v[118:119]
	v_pk_mul_f32 v[106:107], v[2:3], v[120:121]
	s_ashr_i32 s11, s10, 31
	s_lshl_b64 s[4:5], s[10:11], 12
	v_readlane_b32 s0, v116, 0
	v_readlane_b32 s1, v116, 1
	v_readlane_b32 s11, v116, 2
	v_readlane_b32 s12, v116, 3
	v_readlane_b32 s13, v116, 4
	v_readlane_b32 s14, v116, 5
	v_readlane_b32 s18, v116, 6
	v_readlane_b32 s19, v116, 7
	s_nop 1
	v_mul_f32_e32 v4, s0, v4
	v_mul_f32_e32 v5, s0, v5
	v_mul_f32_e32 v6, s0, v6
	v_mul_f32_e32 v7, s0, v7
	v_pk_fma_f32 v[4:5], v[104:105], v[4:5], v[250:251]
	v_pk_fma_f32 v[6:7], v[106:107], v[6:7], v[252:253]
	v_cvt_pk_bf16_f32 v4, v4, v5
	v_cvt_pk_bf16_f32 v5, v6, v7
	v_lshl_add_u64 v[108:109], v[76:77], 0, s[4:5]
	global_store_dwordx2 v[108:109], v[4:5], off
	s_add_u32 s4, s4, 0x1000
	s_addc_u32 s5, s5, 0
	v_mul_f32_e32 v8, s1, v8
	v_mul_f32_e32 v9, s1, v9
	v_mul_f32_e32 v10, s1, v10
	v_mul_f32_e32 v11, s1, v11
	v_pk_fma_f32 v[8:9], v[104:105], v[8:9], v[250:251]
	v_pk_fma_f32 v[10:11], v[106:107], v[10:11], v[252:253]
	v_cvt_pk_bf16_f32 v8, v8, v9
	v_cvt_pk_bf16_f32 v9, v10, v11
	v_lshl_add_u64 v[108:109], v[76:77], 0, s[4:5]
	global_store_dwordx2 v[108:109], v[8:9], off
	s_add_u32 s4, s4, 0x1000
	s_addc_u32 s5, s5, 0
	v_mul_f32_e32 v12, s11, v12
	v_mul_f32_e32 v13, s11, v13
	v_mul_f32_e32 v14, s11, v14
	v_mul_f32_e32 v15, s11, v15
	v_pk_fma_f32 v[12:13], v[104:105], v[12:13], v[250:251]
	v_pk_fma_f32 v[14:15], v[106:107], v[14:15], v[252:253]
	v_cvt_pk_bf16_f32 v12, v12, v13
	v_cvt_pk_bf16_f32 v13, v14, v15
	v_lshl_add_u64 v[108:109], v[76:77], 0, s[4:5]
	global_store_dwordx2 v[108:109], v[12:13], off
	s_add_u32 s4, s4, 0x1000
	s_addc_u32 s5, s5, 0
	v_mul_f32_e32 v16, s12, v16
	v_mul_f32_e32 v17, s12, v17
	v_mul_f32_e32 v18, s12, v18
	v_mul_f32_e32 v19, s12, v19
	v_pk_fma_f32 v[16:17], v[104:105], v[16:17], v[250:251]
	v_pk_fma_f32 v[18:19], v[106:107], v[18:19], v[252:253]
	v_cvt_pk_bf16_f32 v16, v16, v17
	v_cvt_pk_bf16_f32 v17, v18, v19
	v_lshl_add_u64 v[108:109], v[76:77], 0, s[4:5]
	global_store_dwordx2 v[108:109], v[16:17], off
	s_add_u32 s4, s4, 0x1000
	s_addc_u32 s5, s5, 0
	v_mul_f32_e32 v20, s13, v20
	v_mul_f32_e32 v21, s13, v21
	v_mul_f32_e32 v22, s13, v22
	v_mul_f32_e32 v23, s13, v23
	v_pk_fma_f32 v[20:21], v[104:105], v[20:21], v[250:251]
	v_pk_fma_f32 v[22:23], v[106:107], v[22:23], v[252:253]
	v_cvt_pk_bf16_f32 v20, v20, v21
	v_cvt_pk_bf16_f32 v21, v22, v23
	v_lshl_add_u64 v[108:109], v[76:77], 0, s[4:5]
	global_store_dwordx2 v[108:109], v[20:21], off
	s_add_u32 s4, s4, 0x1000
	s_addc_u32 s5, s5, 0
	v_mul_f32_e32 v24, s14, v24
	v_mul_f32_e32 v25, s14, v25
	v_mul_f32_e32 v26, s14, v26
	v_mul_f32_e32 v27, s14, v27
	v_pk_fma_f32 v[24:25], v[104:105], v[24:25], v[250:251]
	v_pk_fma_f32 v[26:27], v[106:107], v[26:27], v[252:253]
	v_cvt_pk_bf16_f32 v24, v24, v25
	v_cvt_pk_bf16_f32 v25, v26, v27
	v_lshl_add_u64 v[108:109], v[76:77], 0, s[4:5]
	global_store_dwordx2 v[108:109], v[24:25], off
	s_add_u32 s4, s4, 0x1000
	s_addc_u32 s5, s5, 0
	v_mul_f32_e32 v28, s18, v28
	v_mul_f32_e32 v29, s18, v29
	v_mul_f32_e32 v30, s18, v30
	v_mul_f32_e32 v31, s18, v31
	v_pk_fma_f32 v[28:29], v[104:105], v[28:29], v[250:251]
	v_pk_fma_f32 v[30:31], v[106:107], v[30:31], v[252:253]
	v_cvt_pk_bf16_f32 v28, v28, v29
	v_cvt_pk_bf16_f32 v29, v30, v31
	v_lshl_add_u64 v[108:109], v[76:77], 0, s[4:5]
	global_store_dwordx2 v[108:109], v[28:29], off
	s_add_u32 s4, s4, 0x1000
	s_addc_u32 s5, s5, 0
	v_mul_f32_e32 v32, s19, v32
	v_mul_f32_e32 v33, s19, v33
	v_mul_f32_e32 v34, s19, v34
	v_mul_f32_e32 v35, s19, v35
	v_pk_fma_f32 v[32:33], v[104:105], v[32:33], v[250:251]
	v_pk_fma_f32 v[34:35], v[106:107], v[34:35], v[252:253]
	v_cvt_pk_bf16_f32 v32, v32, v33
	v_cvt_pk_bf16_f32 v33, v34, v35
	v_lshl_add_u64 v[108:109], v[76:77], 0, s[4:5]
	global_store_dwordx2 v[108:109], v[32:33], off
	s_add_u32 s4, s4, 0x1000
	s_addc_u32 s5, s5, 0
	v_readlane_b32 s0, v116, 8
	v_readlane_b32 s1, v116, 9
	v_readlane_b32 s11, v116, 10
	v_readlane_b32 s12, v116, 11
	v_readlane_b32 s13, v116, 12
	v_readlane_b32 s14, v116, 13
	v_readlane_b32 s18, v116, 14
	v_readlane_b32 s19, v116, 15
	s_nop 1
	v_mul_f32_e32 v36, s0, v36
	v_mul_f32_e32 v37, s0, v37
	v_mul_f32_e32 v38, s0, v38
	v_mul_f32_e32 v39, s0, v39
	v_pk_fma_f32 v[36:37], v[104:105], v[36:37], v[250:251]
	v_pk_fma_f32 v[38:39], v[106:107], v[38:39], v[252:253]
	v_cvt_pk_bf16_f32 v36, v36, v37
	v_cvt_pk_bf16_f32 v37, v38, v39
	v_lshl_add_u64 v[108:109], v[76:77], 0, s[4:5]
	global_store_dwordx2 v[108:109], v[36:37], off
	s_add_u32 s4, s4, 0x1000
	s_addc_u32 s5, s5, 0
	v_mul_f32_e32 v40, s1, v40
	v_mul_f32_e32 v41, s1, v41
	v_mul_f32_e32 v42, s1, v42
	v_mul_f32_e32 v43, s1, v43
	v_pk_fma_f32 v[40:41], v[104:105], v[40:41], v[250:251]
	v_pk_fma_f32 v[42:43], v[106:107], v[42:43], v[252:253]
	v_cvt_pk_bf16_f32 v40, v40, v41
	v_cvt_pk_bf16_f32 v41, v42, v43
	v_lshl_add_u64 v[108:109], v[76:77], 0, s[4:5]
	global_store_dwordx2 v[108:109], v[40:41], off
	s_add_u32 s4, s4, 0x1000
	s_addc_u32 s5, s5, 0
	v_mul_f32_e32 v44, s11, v44
	v_mul_f32_e32 v45, s11, v45
	v_mul_f32_e32 v46, s11, v46
	v_mul_f32_e32 v47, s11, v47
	v_pk_fma_f32 v[44:45], v[104:105], v[44:45], v[250:251]
	v_pk_fma_f32 v[46:47], v[106:107], v[46:47], v[252:253]
	v_cvt_pk_bf16_f32 v44, v44, v45
	v_cvt_pk_bf16_f32 v45, v46, v47
	v_lshl_add_u64 v[108:109], v[76:77], 0, s[4:5]
	global_store_dwordx2 v[108:109], v[44:45], off
	s_add_u32 s4, s4, 0x1000
	s_addc_u32 s5, s5, 0
	v_mul_f32_e32 v48, s12, v48
	v_mul_f32_e32 v49, s12, v49
	v_mul_f32_e32 v50, s12, v50
	v_mul_f32_e32 v51, s12, v51
	v_pk_fma_f32 v[48:49], v[104:105], v[48:49], v[250:251]
	v_pk_fma_f32 v[50:51], v[106:107], v[50:51], v[252:253]
	v_cvt_pk_bf16_f32 v48, v48, v49
	v_cvt_pk_bf16_f32 v49, v50, v51
	v_lshl_add_u64 v[108:109], v[76:77], 0, s[4:5]
	global_store_dwordx2 v[108:109], v[48:49], off
	s_add_u32 s4, s4, 0x1000
	s_addc_u32 s5, s5, 0
	v_mul_f32_e32 v52, s13, v52
	v_mul_f32_e32 v53, s13, v53
	v_mul_f32_e32 v54, s13, v54
	v_mul_f32_e32 v55, s13, v55
	v_pk_fma_f32 v[52:53], v[104:105], v[52:53], v[250:251]
	v_pk_fma_f32 v[54:55], v[106:107], v[54:55], v[252:253]
	v_cvt_pk_bf16_f32 v52, v52, v53
	v_cvt_pk_bf16_f32 v53, v54, v55
	v_lshl_add_u64 v[108:109], v[76:77], 0, s[4:5]
	global_store_dwordx2 v[108:109], v[52:53], off
	s_add_u32 s4, s4, 0x1000
	s_addc_u32 s5, s5, 0
	v_mul_f32_e32 v56, s14, v56
	v_mul_f32_e32 v57, s14, v57
	v_mul_f32_e32 v58, s14, v58
	v_mul_f32_e32 v59, s14, v59
	v_pk_fma_f32 v[56:57], v[104:105], v[56:57], v[250:251]
	v_pk_fma_f32 v[58:59], v[106:107], v[58:59], v[252:253]
	v_cvt_pk_bf16_f32 v56, v56, v57
	v_cvt_pk_bf16_f32 v57, v58, v59
	v_lshl_add_u64 v[108:109], v[76:77], 0, s[4:5]
	global_store_dwordx2 v[108:109], v[56:57], off
	s_add_u32 s4, s4, 0x1000
	s_addc_u32 s5, s5, 0
	v_mul_f32_e32 v60, s18, v60
	v_mul_f32_e32 v61, s18, v61
	v_mul_f32_e32 v62, s18, v62
	v_mul_f32_e32 v63, s18, v63
	v_pk_fma_f32 v[60:61], v[104:105], v[60:61], v[250:251]
	v_pk_fma_f32 v[62:63], v[106:107], v[62:63], v[252:253]
	v_cvt_pk_bf16_f32 v60, v60, v61
	v_cvt_pk_bf16_f32 v61, v62, v63
	v_lshl_add_u64 v[108:109], v[76:77], 0, s[4:5]
	global_store_dwordx2 v[108:109], v[60:61], off
	s_add_u32 s4, s4, 0x1000
	s_addc_u32 s5, s5, 0
	v_mul_f32_e32 v64, s19, v64
	v_mul_f32_e32 v65, s19, v65
	v_mul_f32_e32 v66, s19, v66
	v_mul_f32_e32 v67, s19, v67
	v_pk_fma_f32 v[64:65], v[104:105], v[64:65], v[250:251]
	v_pk_fma_f32 v[66:67], v[106:107], v[66:67], v[252:253]
	v_cvt_pk_bf16_f32 v64, v64, v65
	v_cvt_pk_bf16_f32 v65, v66, v67
	v_lshl_add_u64 v[108:109], v[76:77], 0, s[4:5]
	global_store_dwordx2 v[108:109], v[64:65], off
	s_add_u32 s4, s4, 0x1000
	s_addc_u32 s5, s5, 0
	s_mov_b32 s12, 0x2000
	s_mov_b32 s13, 0
	s_waitcnt lgkmcnt(0)
	s_barrier
	s_add_i32 s22, s22, s34
	s_add_i32 s10, s10, s88
	s_cmpk_gt_i32 s22, 0x3ff
	s_cbranch_scc0 .Lnm_n1_loop
	s_waitcnt vmcnt(0)
	s_barrier
	s_branch .LBB0_182

.LBB0_989:
	v_mbcnt_lo_u32_b32 v112, -1, 0
	v_mbcnt_hi_u32_b32 v112, -1, v112
	v_lshl_add_u32 v93, s3, 6, v112
	v_lshlrev_b32_e32 v93, 4, v93
	v_add_u32_e32 v122, 0x10000, v93
	v_and_b32_e32 v112, 15, v112
	v_lshlrev_b32_e32 v85, 2, v112
	v_add_u32_e32 v85, 0x20100, v85
	s_lshl_b32 s17, s3, 6
	s_add_u32 s17, s17, 0x20100
	v_mov_b32_e32 v84, s17
	s_mov_b32 s12, 0x8000
	s_mov_b32 s13, 0
	s_ashr_i32 s9, s8, 31
	s_lshl_b64 s[0:1], s[8:9], 13
	s_lshl_b32 s10, s3, 10
	s_mov_b32 m0, s10
	v_lshl_add_u64 v[110:111], v[76:77], 0, s[0:1]
	global_load_lds_dwordx4 v[110:111], off
	s_add_u32 s0, s0, 0x2000
	s_addc_u32 s1, s1, 0
	s_add_u32 s10, s10, 0x2000
	s_mov_b32 m0, s10
	v_lshl_add_u64 v[110:111], v[76:77], 0, s[0:1]
	global_load_lds_dwordx4 v[110:111], off
	s_add_u32 s0, s0, 0x2000
	s_addc_u32 s1, s1, 0
	s_add_u32 s10, s10, 0x2000
	s_mov_b32 m0, s10
	v_lshl_add_u64 v[110:111], v[76:77], 0, s[0:1]
	global_load_lds_dwordx4 v[110:111], off
	s_add_u32 s0, s0, 0x2000
	s_addc_u32 s1, s1, 0
	s_add_u32 s10, s10, 0x2000
	s_mov_b32 m0, s10
	v_lshl_add_u64 v[110:111], v[76:77], 0, s[0:1]
	global_load_lds_dwordx4 v[110:111], off
	s_add_u32 s0, s0, 0x2000
	s_addc_u32 s1, s1, 0
	s_add_u32 s10, s10, 0x2000
	s_mov_b32 m0, s10
	v_lshl_add_u64 v[110:111], v[76:77], 0, s[0:1]
	global_load_lds_dwordx4 v[110:111], off
	s_add_u32 s0, s0, 0x2000
	s_addc_u32 s1, s1, 0
	s_add_u32 s10, s10, 0x2000
	s_mov_b32 m0, s10
	v_lshl_add_u64 v[110:111], v[76:77], 0, s[0:1]
	global_load_lds_dwordx4 v[110:111], off
	s_add_u32 s0, s0, 0x2000
	s_addc_u32 s1, s1, 0
	s_add_u32 s10, s10, 0x2000
	s_mov_b32 m0, s10
	v_lshl_add_u64 v[110:111], v[76:77], 0, s[0:1]
	global_load_lds_dwordx4 v[110:111], off
	s_add_u32 s0, s0, 0x2000
	s_addc_u32 s1, s1, 0
	s_add_u32 s10, s10, 0x2000
	s_mov_b32 m0, s10
	v_lshl_add_u64 v[110:111], v[76:77], 0, s[0:1]
	global_load_lds_dwordx4 v[110:111], off
	s_add_u32 s0, s0, 0x2000
	s_addc_u32 s1, s1, 0
	s_add_u32 s10, s10, 0x2000
	s_mov_b32 m0, s10
	v_lshl_add_u64 v[110:111], v[76:77], 0, s[0:1]
	global_load_lds_dwordx4 v[110:111], off
	s_add_u32 s0, s0, 0x2000
	s_addc_u32 s1, s1, 0
	s_add_u32 s10, s10, 0x2000
	s_mov_b32 m0, s10
	v_lshl_add_u64 v[110:111], v[76:77], 0, s[0:1]
	global_load_lds_dwordx4 v[110:111], off
	s_add_u32 s0, s0, 0x2000
	s_addc_u32 s1, s1, 0
	s_add_u32 s10, s10, 0x2000
	s_mov_b32 m0, s10
	v_lshl_add_u64 v[110:111], v[76:77], 0, s[0:1]
	global_load_lds_dwordx4 v[110:111], off
	s_add_u32 s0, s0, 0x2000
	s_addc_u32 s1, s1, 0
	s_add_u32 s10, s10, 0x2000
	s_mov_b32 m0, s10
	v_lshl_add_u64 v[110:111], v[76:77], 0, s[0:1]
	global_load_lds_dwordx4 v[110:111], off
	s_add_u32 s0, s0, 0x2000
	s_addc_u32 s1, s1, 0
	s_add_u32 s10, s10, 0x2000
	s_mov_b32 m0, s10
	v_lshl_add_u64 v[110:111], v[76:77], 0, s[0:1]
	global_load_lds_dwordx4 v[110:111], off
	s_add_u32 s0, s0, 0x2000
	s_addc_u32 s1, s1, 0
	s_add_u32 s10, s10, 0x2000
	s_mov_b32 m0, s10
	v_lshl_add_u64 v[110:111], v[76:77], 0, s[0:1]
	global_load_lds_dwordx4 v[110:111], off
	s_add_u32 s0, s0, 0x2000
	s_addc_u32 s1, s1, 0
	s_add_u32 s10, s10, 0x2000
	s_mov_b32 m0, s10
	v_lshl_add_u64 v[110:111], v[76:77], 0, s[0:1]
	global_load_lds_dwordx4 v[110:111], off
	s_add_u32 s0, s0, 0x2000
	s_addc_u32 s1, s1, 0
	s_add_u32 s10, s10, 0x2000
	s_mov_b32 m0, s10
	v_lshl_add_u64 v[110:111], v[76:77], 0, s[0:1]
	global_load_lds_dwordx4 v[110:111], off
	s_waitcnt vmcnt(0)
.Lnm_n2_loop:
	s_waitcnt vmcnt(16)
	ds_read_b128 v[4:7], v93
	ds_read_b128 v[8:11], v93 offset:8192
	ds_read_b128 v[12:15], v93 offset:16384
	ds_read_b128 v[16:19], v93 offset:24576
	ds_read_b128 v[20:23], v93 offset:32768
	ds_read_b128 v[24:27], v93 offset:40960
	ds_read_b128 v[28:31], v93 offset:49152
	ds_read_b128 v[32:35], v93 offset:57344
	ds_read_b128 v[36:39], v122
	ds_read_b128 v[40:43], v122 offset:8192
	ds_read_b128 v[44:47], v122 offset:16384
	ds_read_b128 v[48:51], v122 offset:24576
	ds_read_b128 v[52:55], v122 offset:32768
	ds_read_b128 v[56:59], v122 offset:40960
	ds_read_b128 v[60:63], v122 offset:49152
	ds_read_b128 v[64:67], v122 offset:57344
	s_ashr_i32 s0, s20, 8
	v_mad_i64_i32 v[110:111], s[0:1], s0, v178, v[82:83]
	v_lshl_add_u64 v[112:113], v[110:111], 0, s[12:13]
	global_load_dwordx4 v[118:121], v[112:113], off
	s_mov_b32 s0, 0x6000
	s_mov_b32 s1, 0
	v_lshl_add_u64 v[112:113], v[110:111], 0, s[0:1]
	global_load_dwordx4 v[250:253], v[112:113], off
	s_waitcnt lgkmcnt(0)
	s_add_i32 s9, s20, s34
	s_add_i32 s10, s8, s88
	s_cmpk_gt_i32 s9, 0x3ff
	s_cselect_b32 s10, s8, s10
	s_ashr_i32 s11, s10, 31
	s_lshl_b64 s[0:1], s[10:11], 13
	s_lshl_b32 s10, s3, 10
	s_mov_b32 m0, s10
	v_lshl_add_u64 v[110:111], v[76:77], 0, s[0:1]
	global_load_lds_dwordx4 v[110:111], off
	s_add_u32 s0, s0, 0x2000
	s_addc_u32 s1, s1, 0
	s_add_u32 s10, s10, 0x2000
	s_mov_b32 m0, s10
	v_lshl_add_u64 v[110:111], v[76:77], 0, s[0:1]
	global_load_lds_dwordx4 v[110:111], off
	s_add_u32 s0, s0, 0x2000
	s_addc_u32 s1, s1, 0
	s_add_u32 s10, s10, 0x2000
	s_mov_b32 m0, s10
	v_lshl_add_u64 v[110:111], v[76:77], 0, s[0:1]
	global_load_lds_dwordx4 v[110:111], off
	s_add_u32 s0, s0, 0x2000
	s_addc_u32 s1, s1, 0
	s_add_u32 s10, s10, 0x2000
	s_mov_b32 m0, s10
	v_lshl_add_u64 v[110:111], v[76:77], 0, s[0:1]
	global_load_lds_dwordx4 v[110:111], off
	s_add_u32 s0, s0, 0x2000
	s_addc_u32 s1, s1, 0
	s_add_u32 s10, s10, 0x2000
	s_mov_b32 m0, s10
	v_lshl_add_u64 v[110:111], v[76:77], 0, s[0:1]
	global_load_lds_dwordx4 v[110:111], off
	s_add_u32 s0, s0, 0x2000
	s_addc_u32 s1, s1, 0
	s_add_u32 s10, s10, 0x2000
	s_mov_b32 m0, s10
	v_lshl_add_u64 v[110:111], v[76:77], 0, s[0:1]
	global_load_lds_dwordx4 v[110:111], off
	s_add_u32 s0, s0, 0x2000
	s_addc_u32 s1, s1, 0
	s_add_u32 s10, s10, 0x2000
	s_mov_b32 m0, s10
	v_lshl_add_u64 v[110:111], v[76:77], 0, s[0:1]
	global_load_lds_dwordx4 v[110:111], off
	s_add_u32 s0, s0, 0x2000
	s_addc_u32 s1, s1, 0
	s_add_u32 s10, s10, 0x2000
	s_mov_b32 m0, s10
	v_lshl_add_u64 v[110:111], v[76:77], 0, s[0:1]
	global_load_lds_dwordx4 v[110:111], off
	s_add_u32 s0, s0, 0x2000
	s_addc_u32 s1, s1, 0
	s_add_u32 s10, s10, 0x2000
	s_mov_b32 m0, s10
	v_lshl_add_u64 v[110:111], v[76:77], 0, s[0:1]
	global_load_lds_dwordx4 v[110:111], off
	s_add_u32 s0, s0, 0x2000
	s_addc_u32 s1, s1, 0
	s_add_u32 s10, s10, 0x2000
	s_mov_b32 m0, s10
	v_lshl_add_u64 v[110:111], v[76:77], 0, s[0:1]
	global_load_lds_dwordx4 v[110:111], off
	s_add_u32 s0, s0, 0x2000
	s_addc_u32 s1, s1, 0
	s_add_u32 s10, s10, 0x2000
	s_mov_b32 m0, s10
	v_lshl_add_u64 v[110:111], v[76:77], 0, s[0:1]
	global_load_lds_dwordx4 v[110:111], off
	s_add_u32 s0, s0, 0x2000
	s_addc_u32 s1, s1, 0
	s_add_u32 s10, s10, 0x2000
	s_mov_b32 m0, s10
	v_lshl_add_u64 v[110:111], v[76:77], 0, s[0:1]
	global_load_lds_dwordx4 v[110:111], off
	s_add_u32 s0, s0, 0x2000
	s_addc_u32 s1, s1, 0
	s_add_u32 s10, s10, 0x2000
	s_mov_b32 m0, s10
	v_lshl_add_u64 v[110:111], v[76:77], 0, s[0:1]
	global_load_lds_dwordx4 v[110:111], off
	s_add_u32 s0, s0, 0x2000
	s_addc_u32 s1, s1, 0
	s_add_u32 s10, s10, 0x2000
	s_mov_b32 m0, s10
	v_lshl_add_u64 v[110:111], v[76:77], 0, s[0:1]
	global_load_lds_dwordx4 v[110:111], off
	s_add_u32 s0, s0, 0x2000
	s_addc_u32 s1, s1, 0
	s_add_u32 s10, s10, 0x2000
	s_mov_b32 m0, s10
	v_lshl_add_u64 v[110:111], v[76:77], 0, s[0:1]
	global_load_lds_dwordx4 v[110:111], off
	s_add_u32 s0, s0, 0x2000
	s_addc_u32 s1, s1, 0
	s_add_u32 s10, s10, 0x2000
	s_mov_b32 m0, s10
	v_lshl_add_u64 v[110:111], v[76:77], 0, s[0:1]
	global_load_lds_dwordx4 v[110:111], off
	v_mul_f32_e32 v68, v5, v5
	v_mul_f32_e32 v102, v7, v7
	v_fmac_f32_e32 v68, v4, v4
	v_fmac_f32_e32 v102, v6, v6
	v_add_f32_e32 v68, v68, v102
	v_mul_f32_e32 v69, v9, v9
	v_mul_f32_e32 v103, v11, v11
	v_fmac_f32_e32 v69, v8, v8
	v_fmac_f32_e32 v103, v10, v10
	v_add_f32_e32 v69, v69, v103
	v_mul_f32_e32 v70, v13, v13
	v_mul_f32_e32 v104, v15, v15
	v_fmac_f32_e32 v70, v12, v12
	v_fmac_f32_e32 v104, v14, v14
	v_add_f32_e32 v70, v70, v104
	v_mul_f32_e32 v71, v17, v17
	v_mul_f32_e32 v105, v19, v19
	v_fmac_f32_e32 v71, v16, v16
	v_fmac_f32_e32 v105, v18, v18
	v_add_f32_e32 v71, v71, v105
	v_mul_f32_e32 v72, v21, v21
	v_mul_f32_e32 v106, v23, v23
	v_fmac_f32_e32 v72, v20, v20
	v_fmac_f32_e32 v106, v22, v22
	v_add_f32_e32 v72, v72, v106
	v_mul_f32_e32 v73, v25, v25
	v_mul_f32_e32 v107, v27, v27
	v_fmac_f32_e32 v73, v24, v24
	v_fmac_f32_e32 v107, v26, v26
	v_add_f32_e32 v73, v73, v107
	v_mul_f32_e32 v74, v29, v29
	v_mul_f32_e32 v108, v31, v31
	v_fmac_f32_e32 v74, v28, v28
	v_fmac_f32_e32 v108, v30, v30
	v_add_f32_e32 v74, v74, v108
	v_mul_f32_e32 v75, v33, v33
	v_mul_f32_e32 v109, v35, v35
	v_fmac_f32_e32 v75, v32, v32
	v_fmac_f32_e32 v109, v34, v34
	v_add_f32_e32 v75, v75, v109
	v_mul_f32_e32 v94, v37, v37
	v_mul_f32_e32 v110, v39, v39
	v_fmac_f32_e32 v94, v36, v36
	v_fmac_f32_e32 v110, v38, v38
	v_add_f32_e32 v94, v94, v110
	v_mul_f32_e32 v95, v41, v41
	v_mul_f32_e32 v111, v43, v43
	v_fmac_f32_e32 v95, v40, v40
	v_fmac_f32_e32 v111, v42, v42
	v_add_f32_e32 v95, v95, v111
	v_mul_f32_e32 v96, v45, v45
	v_mul_f32_e32 v112, v47, v47
	v_fmac_f32_e32 v96, v44, v44
	v_fmac_f32_e32 v112, v46, v46
	v_add_f32_e32 v96, v96, v112
	v_mul_f32_e32 v97, v49, v49
	v_mul_f32_e32 v113, v51, v51
	v_fmac_f32_e32 v97, v48, v48
	v_fmac_f32_e32 v113, v50, v50
	v_add_f32_e32 v97, v97, v113
	v_mul_f32_e32 v98, v53, v53
	v_mul_f32_e32 v114, v55, v55
	v_fmac_f32_e32 v98, v52, v52
	v_fmac_f32_e32 v114, v54, v54
	v_add_f32_e32 v98, v98, v114
	v_mul_f32_e32 v99, v57, v57
	v_mul_f32_e32 v115, v59, v59
	v_fmac_f32_e32 v99, v56, v56
	v_fmac_f32_e32 v115, v58, v58
	v_add_f32_e32 v99, v99, v115
	v_mul_f32_e32 v100, v61, v61
	v_mul_f32_e32 v116, v63, v63
	v_fmac_f32_e32 v100, v60, v60
	v_fmac_f32_e32 v116, v62, v62
	v_add_f32_e32 v100, v100, v116
	v_mul_f32_e32 v101, v65, v65
	v_mul_f32_e32 v117, v67, v67
	v_fmac_f32_e32 v101, v64, v64
	v_fmac_f32_e32 v117, v66, v66
	v_add_f32_e32 v101, v101, v117
	ds_bpermute_b32 v102, v87, v68
	ds_bpermute_b32 v103, v87, v69
	ds_bpermute_b32 v104, v87, v70
	ds_bpermute_b32 v105, v87, v71
	ds_bpermute_b32 v106, v87, v72
	ds_bpermute_b32 v107, v87, v73
	ds_bpermute_b32 v108, v87, v74
	ds_bpermute_b32 v109, v87, v75
	ds_bpermute_b32 v110, v87, v94
	ds_bpermute_b32 v111, v87, v95
	ds_bpermute_b32 v112, v87, v96
	ds_bpermute_b32 v113, v87, v97
	ds_bpermute_b32 v114, v87, v98
	ds_bpermute_b32 v115, v87, v99
	ds_bpermute_b32 v116, v87, v100
	ds_bpermute_b32 v117, v87, v101
	s_waitcnt lgkmcnt(15)
	v_add_f32_e32 v68, v68, v102
	s_waitcnt lgkmcnt(14)
	v_add_f32_e32 v69, v69, v103
	s_waitcnt lgkmcnt(13)
	v_add_f32_e32 v70, v70, v104
	s_waitcnt lgkmcnt(12)
	v_add_f32_e32 v71, v71, v105
	s_waitcnt lgkmcnt(11)
	v_add_f32_e32 v72, v72, v106
	s_waitcnt lgkmcnt(10)
	v_add_f32_e32 v73, v73, v107
	s_waitcnt lgkmcnt(9)
	v_add_f32_e32 v74, v74, v108
	s_waitcnt lgkmcnt(8)
	v_add_f32_e32 v75, v75, v109
	s_waitcnt lgkmcnt(7)
	v_add_f32_e32 v94, v94, v110
	s_waitcnt lgkmcnt(6)
	v_add_f32_e32 v95, v95, v111
	s_waitcnt lgkmcnt(5)
	v_add_f32_e32 v96, v96, v112
	s_waitcnt lgkmcnt(4)
	v_add_f32_e32 v97, v97, v113
	s_waitcnt lgkmcnt(3)
	v_add_f32_e32 v98, v98, v114
	s_waitcnt lgkmcnt(2)
	v_add_f32_e32 v99, v99, v115
	s_waitcnt lgkmcnt(1)
	v_add_f32_e32 v100, v100, v116
	s_waitcnt lgkmcnt(0)
	v_add_f32_e32 v101, v101, v117
	ds_bpermute_b32 v102, v88, v68
	ds_bpermute_b32 v103, v88, v69
	ds_bpermute_b32 v104, v88, v70
	ds_bpermute_b32 v105, v88, v71
	ds_bpermute_b32 v106, v88, v72
	ds_bpermute_b32 v107, v88, v73
	ds_bpermute_b32 v108, v88, v74
	ds_bpermute_b32 v109, v88, v75
	ds_bpermute_b32 v110, v88, v94
	ds_bpermute_b32 v111, v88, v95
	ds_bpermute_b32 v112, v88, v96
	ds_bpermute_b32 v113, v88, v97
	ds_bpermute_b32 v114, v88, v98
	ds_bpermute_b32 v115, v88, v99
	ds_bpermute_b32 v116, v88, v100
	ds_bpermute_b32 v117, v88, v101
	s_waitcnt lgkmcnt(15)
	v_add_f32_e32 v68, v68, v102
	s_waitcnt lgkmcnt(14)
	v_add_f32_e32 v69, v69, v103
	s_waitcnt lgkmcnt(13)
	v_add_f32_e32 v70, v70, v104
	s_waitcnt lgkmcnt(12)
	v_add_f32_e32 v71, v71, v105
	s_waitcnt lgkmcnt(11)
	v_add_f32_e32 v72, v72, v106
	s_waitcnt lgkmcnt(10)
	v_add_f32_e32 v73, v73, v107
	s_waitcnt lgkmcnt(9)
	v_add_f32_e32 v74, v74, v108
	s_waitcnt lgkmcnt(8)
	v_add_f32_e32 v75, v75, v109
	s_waitcnt lgkmcnt(7)
	v_add_f32_e32 v94, v94, v110
	s_waitcnt lgkmcnt(6)
	v_add_f32_e32 v95, v95, v111
	s_waitcnt lgkmcnt(5)
	v_add_f32_e32 v96, v96, v112
	s_waitcnt lgkmcnt(4)
	v_add_f32_e32 v97, v97, v113
	s_waitcnt lgkmcnt(3)
	v_add_f32_e32 v98, v98, v114
	s_waitcnt lgkmcnt(2)
	v_add_f32_e32 v99, v99, v115
	s_waitcnt lgkmcnt(1)
	v_add_f32_e32 v100, v100, v116
	s_waitcnt lgkmcnt(0)
	v_add_f32_e32 v101, v101, v117
	ds_bpermute_b32 v102, v89, v68
	ds_bpermute_b32 v103, v89, v69
	ds_bpermute_b32 v104, v89, v70
	ds_bpermute_b32 v105, v89, v71
	ds_bpermute_b32 v106, v89, v72
	ds_bpermute_b32 v107, v89, v73
	ds_bpermute_b32 v108, v89, v74
	ds_bpermute_b32 v109, v89, v75
	ds_bpermute_b32 v110, v89, v94
	ds_bpermute_b32 v111, v89, v95
	ds_bpermute_b32 v112, v89, v96
	ds_bpermute_b32 v113, v89, v97
	ds_bpermute_b32 v114, v89, v98
	ds_bpermute_b32 v115, v89, v99
	ds_bpermute_b32 v116, v89, v100
	ds_bpermute_b32 v117, v89, v101
	s_waitcnt lgkmcnt(15)
	v_add_f32_e32 v68, v68, v102
	s_waitcnt lgkmcnt(14)
	v_add_f32_e32 v69, v69, v103
	s_waitcnt lgkmcnt(13)
	v_add_f32_e32 v70, v70, v104
	s_waitcnt lgkmcnt(12)
	v_add_f32_e32 v71, v71, v105
	s_waitcnt lgkmcnt(11)
	v_add_f32_e32 v72, v72, v106
	s_waitcnt lgkmcnt(10)
	v_add_f32_e32 v73, v73, v107
	s_waitcnt lgkmcnt(9)
	v_add_f32_e32 v74, v74, v108
	s_waitcnt lgkmcnt(8)
	v_add_f32_e32 v75, v75, v109
	s_waitcnt lgkmcnt(7)
	v_add_f32_e32 v94, v94, v110
	s_waitcnt lgkmcnt(6)
	v_add_f32_e32 v95, v95, v111
	s_waitcnt lgkmcnt(5)
	v_add_f32_e32 v96, v96, v112
	s_waitcnt lgkmcnt(4)
	v_add_f32_e32 v97, v97, v113
	s_waitcnt lgkmcnt(3)
	v_add_f32_e32 v98, v98, v114
	s_waitcnt lgkmcnt(2)
	v_add_f32_e32 v99, v99, v115
	s_waitcnt lgkmcnt(1)
	v_add_f32_e32 v100, v100, v116
	s_waitcnt lgkmcnt(0)
	v_add_f32_e32 v101, v101, v117
	ds_bpermute_b32 v102, v90, v68
	ds_bpermute_b32 v103, v90, v69
	ds_bpermute_b32 v104, v90, v70
	ds_bpermute_b32 v105, v90, v71
	ds_bpermute_b32 v106, v90, v72
	ds_bpermute_b32 v107, v90, v73
	ds_bpermute_b32 v108, v90, v74
	ds_bpermute_b32 v109, v90, v75
	ds_bpermute_b32 v110, v90, v94
	ds_bpermute_b32 v111, v90, v95
	ds_bpermute_b32 v112, v90, v96
	ds_bpermute_b32 v113, v90, v97
	ds_bpermute_b32 v114, v90, v98
	ds_bpermute_b32 v115, v90, v99
	ds_bpermute_b32 v116, v90, v100
	ds_bpermute_b32 v117, v90, v101
	s_waitcnt lgkmcnt(15)
	v_add_f32_e32 v68, v68, v102
	s_waitcnt lgkmcnt(14)
	v_add_f32_e32 v69, v69, v103
	s_waitcnt lgkmcnt(13)
	v_add_f32_e32 v70, v70, v104
	s_waitcnt lgkmcnt(12)
	v_add_f32_e32 v71, v71, v105
	s_waitcnt lgkmcnt(11)
	v_add_f32_e32 v72, v72, v106
	s_waitcnt lgkmcnt(10)
	v_add_f32_e32 v73, v73, v107
	s_waitcnt lgkmcnt(9)
	v_add_f32_e32 v74, v74, v108
	s_waitcnt lgkmcnt(8)
	v_add_f32_e32 v75, v75, v109
	s_waitcnt lgkmcnt(7)
	v_add_f32_e32 v94, v94, v110
	s_waitcnt lgkmcnt(6)
	v_add_f32_e32 v95, v95, v111
	s_waitcnt lgkmcnt(5)
	v_add_f32_e32 v96, v96, v112
	s_waitcnt lgkmcnt(4)
	v_add_f32_e32 v97, v97, v113
	s_waitcnt lgkmcnt(3)
	v_add_f32_e32 v98, v98, v114
	s_waitcnt lgkmcnt(2)
	v_add_f32_e32 v99, v99, v115
	s_waitcnt lgkmcnt(1)
	v_add_f32_e32 v100, v100, v116
	s_waitcnt lgkmcnt(0)
	v_add_f32_e32 v101, v101, v117
	ds_bpermute_b32 v102, v91, v68
	ds_bpermute_b32 v103, v91, v69
	ds_bpermute_b32 v104, v91, v70
	ds_bpermute_b32 v105, v91, v71
	ds_bpermute_b32 v106, v91, v72
	ds_bpermute_b32 v107, v91, v73
	ds_bpermute_b32 v108, v91, v74
	ds_bpermute_b32 v109, v91, v75
	ds_bpermute_b32 v110, v91, v94
	ds_bpermute_b32 v111, v91, v95
	ds_bpermute_b32 v112, v91, v96
	ds_bpermute_b32 v113, v91, v97
	ds_bpermute_b32 v114, v91, v98
	ds_bpermute_b32 v115, v91, v99
	ds_bpermute_b32 v116, v91, v100
	ds_bpermute_b32 v117, v91, v101
	s_waitcnt lgkmcnt(15)
	v_add_f32_e32 v68, v68, v102
	s_waitcnt lgkmcnt(14)
	v_add_f32_e32 v69, v69, v103
	s_waitcnt lgkmcnt(13)
	v_add_f32_e32 v70, v70, v104
	s_waitcnt lgkmcnt(12)
	v_add_f32_e32 v71, v71, v105
	s_waitcnt lgkmcnt(11)
	v_add_f32_e32 v72, v72, v106
	s_waitcnt lgkmcnt(10)
	v_add_f32_e32 v73, v73, v107
	s_waitcnt lgkmcnt(9)
	v_add_f32_e32 v74, v74, v108
	s_waitcnt lgkmcnt(8)
	v_add_f32_e32 v75, v75, v109
	s_waitcnt lgkmcnt(7)
	v_add_f32_e32 v94, v94, v110
	s_waitcnt lgkmcnt(6)
	v_add_f32_e32 v95, v95, v111
	s_waitcnt lgkmcnt(5)
	v_add_f32_e32 v96, v96, v112
	s_waitcnt lgkmcnt(4)
	v_add_f32_e32 v97, v97, v113
	s_waitcnt lgkmcnt(3)
	v_add_f32_e32 v98, v98, v114
	s_waitcnt lgkmcnt(2)
	v_add_f32_e32 v99, v99, v115
	s_waitcnt lgkmcnt(1)
	v_add_f32_e32 v100, v100, v116
	s_waitcnt lgkmcnt(0)
	v_add_f32_e32 v101, v101, v117
	ds_bpermute_b32 v102, v92, v68
	ds_bpermute_b32 v103, v92, v69
	ds_bpermute_b32 v104, v92, v70
	ds_bpermute_b32 v105, v92, v71
	ds_bpermute_b32 v106, v92, v72
	ds_bpermute_b32 v107, v92, v73
	ds_bpermute_b32 v108, v92, v74
	ds_bpermute_b32 v109, v92, v75
	ds_bpermute_b32 v110, v92, v94
	ds_bpermute_b32 v111, v92, v95
	ds_bpermute_b32 v112, v92, v96
	ds_bpermute_b32 v113, v92, v97
	ds_bpermute_b32 v114, v92, v98
	ds_bpermute_b32 v115, v92, v99
	ds_bpermute_b32 v116, v92, v100
	ds_bpermute_b32 v117, v92, v101
	s_waitcnt lgkmcnt(15)
	v_add_f32_e32 v68, v68, v102
	s_waitcnt lgkmcnt(14)
	v_add_f32_e32 v69, v69, v103
	s_waitcnt lgkmcnt(13)
	v_add_f32_e32 v70, v70, v104
	s_waitcnt lgkmcnt(12)
	v_add_f32_e32 v71, v71, v105
	s_waitcnt lgkmcnt(11)
	v_add_f32_e32 v72, v72, v106
	s_waitcnt lgkmcnt(10)
	v_add_f32_e32 v73, v73, v107
	s_waitcnt lgkmcnt(9)
	v_add_f32_e32 v74, v74, v108
	s_waitcnt lgkmcnt(8)
	v_add_f32_e32 v75, v75, v109
	s_waitcnt lgkmcnt(7)
	v_add_f32_e32 v94, v94, v110
	s_waitcnt lgkmcnt(6)
	v_add_f32_e32 v95, v95, v111
	s_waitcnt lgkmcnt(5)
	v_add_f32_e32 v96, v96, v112
	s_waitcnt lgkmcnt(4)
	v_add_f32_e32 v97, v97, v113
	s_waitcnt lgkmcnt(3)
	v_add_f32_e32 v98, v98, v114
	s_waitcnt lgkmcnt(2)
	v_add_f32_e32 v99, v99, v115
	s_waitcnt lgkmcnt(1)
	v_add_f32_e32 v100, v100, v116
	s_waitcnt lgkmcnt(0)
	v_add_f32_e32 v101, v101, v117
	s_mov_b64 exec, 1
	ds_write_b128 v84, v[68:71]
	ds_write_b128 v84, v[72:75] offset:16
	ds_write_b128 v84, v[94:97] offset:32
	ds_write_b128 v84, v[98:101] offset:48
	s_mov_b64 exec, -1
	s_waitcnt lgkmcnt(0)
	s_barrier
	ds_read_b32 v102, v85
	ds_read_b32 v103, v85 offset:64
	ds_read_b32 v104, v85 offset:128
	ds_read_b32 v105, v85 offset:192
	ds_read_b32 v106, v85 offset:256
	ds_read_b32 v107, v85 offset:320
	ds_read_b32 v108, v85 offset:384
	ds_read_b32 v109, v85 offset:448
	s_waitcnt lgkmcnt(0)
	v_add_f32_e32 v102, v102, v103
	v_add_f32_e32 v104, v104, v105
	v_add_f32_e32 v106, v106, v107
	v_add_f32_e32 v108, v108, v109
	v_add_f32_e32 v102, v102, v104
	v_add_f32_e32 v106, v106, v108
	v_add_f32_e32 v102, v102, v106
	v_fmamk_f32 v102, v102, 0x3a000000, v173
	v_cmp_gt_f32_e32 vcc, s33, v102
	v_mul_f32_e32 v116, 0x4f800000, v102
	s_nop 1
	v_cndmask_b32_e32 v102, v102, v116, vcc
	v_sqrt_f32_e32 v116, v102
	s_nop 1
	v_add_u32_e32 v111, -1, v116
	v_fma_f32 v112, -v111, v116, v102
	v_cmp_ge_f32_e64 s[14:15], 0, v112
	v_add_u32_e32 v112, 1, v116
	s_nop 1
	v_cndmask_b32_e64 v111, v116, v111, s[14:15]
	v_fma_f32 v116, -v112, v116, v102
	v_cmp_lt_f32_e64 s[14:15], 0, v116
	s_nop 1
	v_cndmask_b32_e64 v116, v111, v112, s[14:15]
	v_mul_f32_e32 v111, 0x37800000, v116
	v_cndmask_b32_e32 v116, v116, v111, vcc
	v_cmp_class_f32_e32 vcc, v102, v174
	s_nop 1
	v_cndmask_b32_e32 v102, v116, v102, vcc
	v_div_scale_f32 v116, s[16:17], v102, v102, 1.0
	v_rcp_f32_e32 v111, v116
	s_nop 0
	v_fma_f32 v112, -v116, v111, 1.0
	v_fmac_f32_e32 v111, v112, v111
	v_div_scale_f32 v112, vcc, 1.0, v102, 1.0
	v_mul_f32_e32 v113, v112, v111
	v_fma_f32 v114, -v116, v113, v112
	v_fmac_f32_e32 v113, v114, v111
	v_fma_f32 v116, -v116, v113, v112
	v_div_fmas_f32 v116, v116, v111, v113
	v_div_fixup_f32 v116, v116, v102, 1.0
	s_waitcnt vmcnt(16)
	v_pk_add_f32 v[118:119], v[118:119], 1.0 op_sel_hi:[1,0]
	v_pk_add_f32 v[120:121], v[120:121], 1.0 op_sel_hi:[1,0]
	v_pk_mul_f32 v[104:105], v[0:1], v[118:119]
	v_pk_mul_f32 v[106:107], v[2:3], v[120:121]
	s_ashr_i32 s9, s8, 31
	s_lshl_b64 s[6:7], s[8:9], 12
	v_readlane_b32 s0, v116, 0
	v_readlane_b32 s1, v116, 1
	v_readlane_b32 s9, v116, 2
	v_readlane_b32 s10, v116, 3
	v_readlane_b32 s11, v116, 4
	v_readlane_b32 s12, v116, 5
	v_readlane_b32 s13, v116, 6
	v_readlane_b32 s14, v116, 7
	s_nop 1
	v_mul_f32_e32 v4, s0, v4
	v_mul_f32_e32 v5, s0, v5
	v_mul_f32_e32 v6, s0, v6
	v_mul_f32_e32 v7, s0, v7
	v_pk_fma_f32 v[4:5], v[104:105], v[4:5], v[250:251]
	v_pk_fma_f32 v[6:7], v[106:107], v[6:7], v[252:253]
	v_cvt_pk_bf16_f32 v4, v4, v5
	v_cvt_pk_bf16_f32 v5, v6, v7
	v_lshl_add_u64 v[108:109], v[78:79], 0, s[6:7]
	global_store_dwordx2 v[108:109], v[4:5], off
	s_add_u32 s6, s6, 0x1000
	s_addc_u32 s7, s7, 0
	v_mul_f32_e32 v8, s1, v8
	v_mul_f32_e32 v9, s1, v9
	v_mul_f32_e32 v10, s1, v10
	v_mul_f32_e32 v11, s1, v11
	v_pk_fma_f32 v[8:9], v[104:105], v[8:9], v[250:251]
	v_pk_fma_f32 v[10:11], v[106:107], v[10:11], v[252:253]
	v_cvt_pk_bf16_f32 v8, v8, v9
	v_cvt_pk_bf16_f32 v9, v10, v11
	v_lshl_add_u64 v[108:109], v[78:79], 0, s[6:7]
	global_store_dwordx2 v[108:109], v[8:9], off
	s_add_u32 s6, s6, 0x1000
	s_addc_u32 s7, s7, 0
	v_mul_f32_e32 v12, s9, v12
	v_mul_f32_e32 v13, s9, v13
	v_mul_f32_e32 v14, s9, v14
	v_mul_f32_e32 v15, s9, v15
	v_pk_fma_f32 v[12:13], v[104:105], v[12:13], v[250:251]
	v_pk_fma_f32 v[14:15], v[106:107], v[14:15], v[252:253]
	v_cvt_pk_bf16_f32 v12, v12, v13
	v_cvt_pk_bf16_f32 v13, v14, v15
	v_lshl_add_u64 v[108:109], v[78:79], 0, s[6:7]
	global_store_dwordx2 v[108:109], v[12:13], off
	s_add_u32 s6, s6, 0x1000
	s_addc_u32 s7, s7, 0
	v_mul_f32_e32 v16, s10, v16
	v_mul_f32_e32 v17, s10, v17
	v_mul_f32_e32 v18, s10, v18
	v_mul_f32_e32 v19, s10, v19
	v_pk_fma_f32 v[16:17], v[104:105], v[16:17], v[250:251]
	v_pk_fma_f32 v[18:19], v[106:107], v[18:19], v[252:253]
	v_cvt_pk_bf16_f32 v16, v16, v17
	v_cvt_pk_bf16_f32 v17, v18, v19
	v_lshl_add_u64 v[108:109], v[78:79], 0, s[6:7]
	global_store_dwordx2 v[108:109], v[16:17], off
	s_add_u32 s6, s6, 0x1000
	s_addc_u32 s7, s7, 0
	v_mul_f32_e32 v20, s11, v20
	v_mul_f32_e32 v21, s11, v21
	v_mul_f32_e32 v22, s11, v22
	v_mul_f32_e32 v23, s11, v23
	v_pk_fma_f32 v[20:21], v[104:105], v[20:21], v[250:251]
	v_pk_fma_f32 v[22:23], v[106:107], v[22:23], v[252:253]
	v_cvt_pk_bf16_f32 v20, v20, v21
	v_cvt_pk_bf16_f32 v21, v22, v23
	v_lshl_add_u64 v[108:109], v[78:79], 0, s[6:7]
	global_store_dwordx2 v[108:109], v[20:21], off
	s_add_u32 s6, s6, 0x1000
	s_addc_u32 s7, s7, 0
	v_mul_f32_e32 v24, s12, v24
	v_mul_f32_e32 v25, s12, v25
	v_mul_f32_e32 v26, s12, v26
	v_mul_f32_e32 v27, s12, v27
	v_pk_fma_f32 v[24:25], v[104:105], v[24:25], v[250:251]
	v_pk_fma_f32 v[26:27], v[106:107], v[26:27], v[252:253]
	v_cvt_pk_bf16_f32 v24, v24, v25
	v_cvt_pk_bf16_f32 v25, v26, v27
	v_lshl_add_u64 v[108:109], v[78:79], 0, s[6:7]
	global_store_dwordx2 v[108:109], v[24:25], off
	s_add_u32 s6, s6, 0x1000
	s_addc_u32 s7, s7, 0
	v_mul_f32_e32 v28, s13, v28
	v_mul_f32_e32 v29, s13, v29
	v_mul_f32_e32 v30, s13, v30
	v_mul_f32_e32 v31, s13, v31
	v_pk_fma_f32 v[28:29], v[104:105], v[28:29], v[250:251]
	v_pk_fma_f32 v[30:31], v[106:107], v[30:31], v[252:253]
	v_cvt_pk_bf16_f32 v28, v28, v29
	v_cvt_pk_bf16_f32 v29, v30, v31
	v_lshl_add_u64 v[108:109], v[78:79], 0, s[6:7]
	global_store_dwordx2 v[108:109], v[28:29], off
	s_add_u32 s6, s6, 0x1000
	s_addc_u32 s7, s7, 0
	v_mul_f32_e32 v32, s14, v32
	v_mul_f32_e32 v33, s14, v33
	v_mul_f32_e32 v34, s14, v34
	v_mul_f32_e32 v35, s14, v35
	v_pk_fma_f32 v[32:33], v[104:105], v[32:33], v[250:251]
	v_pk_fma_f32 v[34:35], v[106:107], v[34:35], v[252:253]
	v_cvt_pk_bf16_f32 v32, v32, v33
	v_cvt_pk_bf16_f32 v33, v34, v35
	v_lshl_add_u64 v[108:109], v[78:79], 0, s[6:7]
	global_store_dwordx2 v[108:109], v[32:33], off
	s_add_u32 s6, s6, 0x1000
	s_addc_u32 s7, s7, 0
	v_readlane_b32 s0, v116, 8
	v_readlane_b32 s1, v116, 9
	v_readlane_b32 s9, v116, 10
	v_readlane_b32 s10, v116, 11
	v_readlane_b32 s11, v116, 12
	v_readlane_b32 s12, v116, 13
	v_readlane_b32 s13, v116, 14
	v_readlane_b32 s14, v116, 15
	s_nop 1
	v_mul_f32_e32 v36, s0, v36
	v_mul_f32_e32 v37, s0, v37
	v_mul_f32_e32 v38, s0, v38
	v_mul_f32_e32 v39, s0, v39
	v_pk_fma_f32 v[36:37], v[104:105], v[36:37], v[250:251]
	v_pk_fma_f32 v[38:39], v[106:107], v[38:39], v[252:253]
	v_cvt_pk_bf16_f32 v36, v36, v37
	v_cvt_pk_bf16_f32 v37, v38, v39
	v_lshl_add_u64 v[108:109], v[78:79], 0, s[6:7]
	global_store_dwordx2 v[108:109], v[36:37], off
	s_add_u32 s6, s6, 0x1000
	s_addc_u32 s7, s7, 0
	v_mul_f32_e32 v40, s1, v40
	v_mul_f32_e32 v41, s1, v41
	v_mul_f32_e32 v42, s1, v42
	v_mul_f32_e32 v43, s1, v43
	v_pk_fma_f32 v[40:41], v[104:105], v[40:41], v[250:251]
	v_pk_fma_f32 v[42:43], v[106:107], v[42:43], v[252:253]
	v_cvt_pk_bf16_f32 v40, v40, v41
	v_cvt_pk_bf16_f32 v41, v42, v43
	v_lshl_add_u64 v[108:109], v[78:79], 0, s[6:7]
	global_store_dwordx2 v[108:109], v[40:41], off
	s_add_u32 s6, s6, 0x1000
	s_addc_u32 s7, s7, 0
	v_mul_f32_e32 v44, s9, v44
	v_mul_f32_e32 v45, s9, v45
	v_mul_f32_e32 v46, s9, v46
	v_mul_f32_e32 v47, s9, v47
	v_pk_fma_f32 v[44:45], v[104:105], v[44:45], v[250:251]
	v_pk_fma_f32 v[46:47], v[106:107], v[46:47], v[252:253]
	v_cvt_pk_bf16_f32 v44, v44, v45
	v_cvt_pk_bf16_f32 v45, v46, v47
	v_lshl_add_u64 v[108:109], v[78:79], 0, s[6:7]
	global_store_dwordx2 v[108:109], v[44:45], off
	s_add_u32 s6, s6, 0x1000
	s_addc_u32 s7, s7, 0
	v_mul_f32_e32 v48, s10, v48
	v_mul_f32_e32 v49, s10, v49
	v_mul_f32_e32 v50, s10, v50
	v_mul_f32_e32 v51, s10, v51
	v_pk_fma_f32 v[48:49], v[104:105], v[48:49], v[250:251]
	v_pk_fma_f32 v[50:51], v[106:107], v[50:51], v[252:253]
	v_cvt_pk_bf16_f32 v48, v48, v49
	v_cvt_pk_bf16_f32 v49, v50, v51
	v_lshl_add_u64 v[108:109], v[78:79], 0, s[6:7]
	global_store_dwordx2 v[108:109], v[48:49], off
	s_add_u32 s6, s6, 0x1000
	s_addc_u32 s7, s7, 0
	v_mul_f32_e32 v52, s11, v52
	v_mul_f32_e32 v53, s11, v53
	v_mul_f32_e32 v54, s11, v54
	v_mul_f32_e32 v55, s11, v55
	v_pk_fma_f32 v[52:53], v[104:105], v[52:53], v[250:251]
	v_pk_fma_f32 v[54:55], v[106:107], v[54:55], v[252:253]
	v_cvt_pk_bf16_f32 v52, v52, v53
	v_cvt_pk_bf16_f32 v53, v54, v55
	v_lshl_add_u64 v[108:109], v[78:79], 0, s[6:7]
	global_store_dwordx2 v[108:109], v[52:53], off
	s_add_u32 s6, s6, 0x1000
	s_addc_u32 s7, s7, 0
	v_mul_f32_e32 v56, s12, v56
	v_mul_f32_e32 v57, s12, v57
	v_mul_f32_e32 v58, s12, v58
	v_mul_f32_e32 v59, s12, v59
	v_pk_fma_f32 v[56:57], v[104:105], v[56:57], v[250:251]
	v_pk_fma_f32 v[58:59], v[106:107], v[58:59], v[252:253]
	v_cvt_pk_bf16_f32 v56, v56, v57
	v_cvt_pk_bf16_f32 v57, v58, v59
	v_lshl_add_u64 v[108:109], v[78:79], 0, s[6:7]
	global_store_dwordx2 v[108:109], v[56:57], off
	s_add_u32 s6, s6, 0x1000
	s_addc_u32 s7, s7, 0
	v_mul_f32_e32 v60, s13, v60
	v_mul_f32_e32 v61, s13, v61
	v_mul_f32_e32 v62, s13, v62
	v_mul_f32_e32 v63, s13, v63
	v_pk_fma_f32 v[60:61], v[104:105], v[60:61], v[250:251]
	v_pk_fma_f32 v[62:63], v[106:107], v[62:63], v[252:253]
	v_cvt_pk_bf16_f32 v60, v60, v61
	v_cvt_pk_bf16_f32 v61, v62, v63
	v_lshl_add_u64 v[108:109], v[78:79], 0, s[6:7]
	global_store_dwordx2 v[108:109], v[60:61], off
	s_add_u32 s6, s6, 0x1000
	s_addc_u32 s7, s7, 0
	v_mul_f32_e32 v64, s14, v64
	v_mul_f32_e32 v65, s14, v65
	v_mul_f32_e32 v66, s14, v66
	v_mul_f32_e32 v67, s14, v67
	v_pk_fma_f32 v[64:65], v[104:105], v[64:65], v[250:251]
	v_pk_fma_f32 v[66:67], v[106:107], v[66:67], v[252:253]
	v_cvt_pk_bf16_f32 v64, v64, v65
	v_cvt_pk_bf16_f32 v65, v66, v67
	v_lshl_add_u64 v[108:109], v[78:79], 0, s[6:7]
	global_store_dwordx2 v[108:109], v[64:65], off
	s_add_u32 s6, s6, 0x1000
	s_addc_u32 s7, s7, 0
	s_mov_b32 s12, 0x8000
	s_mov_b32 s13, 0
	s_waitcnt lgkmcnt(0)
	s_barrier
	s_add_i32 s20, s20, s34
	s_add_i32 s8, s8, s88
	s_cmpk_gt_i32 s20, 0x3ff
	s_cbranch_scc0 .Lnm_n2_loop
	s_waitcnt vmcnt(0)
	s_barrier
	s_branch .LBB0_1048

.LBB0_1323:
	v_mbcnt_lo_u32_b32 v119, -1, 0
	v_mbcnt_hi_u32_b32 v119, -1, v119
	s_lshr_b32 s26, s3, 2
	v_lshl_add_u32 v136, s26, 6, v119
	v_lshlrev_b32_e32 v136, 4, v136
	v_add_u32_e32 v137, 0x10000, v136
	v_and_b32_e32 v119, 15, v119
	v_lshlrev_b32_e32 v117, 2, v119
	v_add_u32_e32 v117, 0x20100, v117
	s_lshl_b32 s10, s26, 6
	s_add_u32 s10, s10, 0x20100
	v_mov_b32_e32 v116, s10
	s_add_i32 s8, s4, -15
	s_ashr_i32 s9, s8, 31
	s_lshl_b64 s[10:11], s[8:9], 13
	s_lshl_b32 s27, s26, 10
	s_mov_b32 m0, s27
	v_lshl_add_u64 v[124:125], v[68:69], 0, s[10:11]
	global_load_lds_dwordx4 v[124:125], off
	s_add_u32 s10, s10, 0x2000
	s_addc_u32 s11, s11, 0
	s_add_u32 s27, s27, 0x2000
	s_mov_b32 m0, s27
	v_lshl_add_u64 v[124:125], v[68:69], 0, s[10:11]
	global_load_lds_dwordx4 v[124:125], off
	s_add_u32 s10, s10, 0x2000
	s_addc_u32 s11, s11, 0
	s_add_u32 s27, s27, 0x2000
	s_mov_b32 m0, s27
	v_lshl_add_u64 v[124:125], v[68:69], 0, s[10:11]
	global_load_lds_dwordx4 v[124:125], off
	s_add_u32 s10, s10, 0x2000
	s_addc_u32 s11, s11, 0
	s_add_u32 s27, s27, 0x2000
	s_mov_b32 m0, s27
	v_lshl_add_u64 v[124:125], v[68:69], 0, s[10:11]
	global_load_lds_dwordx4 v[124:125], off
	s_add_u32 s10, s10, 0x2000
	s_addc_u32 s11, s11, 0
	s_add_u32 s27, s27, 0x2000
	s_mov_b32 m0, s27
	v_lshl_add_u64 v[124:125], v[68:69], 0, s[10:11]
	global_load_lds_dwordx4 v[124:125], off
	s_add_u32 s10, s10, 0x2000
	s_addc_u32 s11, s11, 0
	s_add_u32 s27, s27, 0x2000
	s_mov_b32 m0, s27
	v_lshl_add_u64 v[124:125], v[68:69], 0, s[10:11]
	global_load_lds_dwordx4 v[124:125], off
	s_add_u32 s10, s10, 0x2000
	s_addc_u32 s11, s11, 0
	s_add_u32 s27, s27, 0x2000
	s_mov_b32 m0, s27
	v_lshl_add_u64 v[124:125], v[68:69], 0, s[10:11]
	global_load_lds_dwordx4 v[124:125], off
	s_add_u32 s10, s10, 0x2000
	s_addc_u32 s11, s11, 0
	s_add_u32 s27, s27, 0x2000
	s_mov_b32 m0, s27
	v_lshl_add_u64 v[124:125], v[68:69], 0, s[10:11]
	global_load_lds_dwordx4 v[124:125], off
	s_add_u32 s10, s10, 0x2000
	s_addc_u32 s11, s11, 0
	s_add_u32 s27, s27, 0x2000
	s_mov_b32 m0, s27
	v_lshl_add_u64 v[124:125], v[68:69], 0, s[10:11]
	global_load_lds_dwordx4 v[124:125], off
	s_add_u32 s10, s10, 0x2000
	s_addc_u32 s11, s11, 0
	s_add_u32 s27, s27, 0x2000
	s_mov_b32 m0, s27
	v_lshl_add_u64 v[124:125], v[68:69], 0, s[10:11]
	global_load_lds_dwordx4 v[124:125], off
	s_add_u32 s10, s10, 0x2000
	s_addc_u32 s11, s11, 0
	s_add_u32 s27, s27, 0x2000
	s_mov_b32 m0, s27
	v_lshl_add_u64 v[124:125], v[68:69], 0, s[10:11]
	global_load_lds_dwordx4 v[124:125], off
	s_add_u32 s10, s10, 0x2000
	s_addc_u32 s11, s11, 0
	s_add_u32 s27, s27, 0x2000
	s_mov_b32 m0, s27
	v_lshl_add_u64 v[124:125], v[68:69], 0, s[10:11]
	global_load_lds_dwordx4 v[124:125], off
	s_add_u32 s10, s10, 0x2000
	s_addc_u32 s11, s11, 0
	s_add_u32 s27, s27, 0x2000
	s_mov_b32 m0, s27
	v_lshl_add_u64 v[124:125], v[68:69], 0, s[10:11]
	global_load_lds_dwordx4 v[124:125], off
	s_add_u32 s10, s10, 0x2000
	s_addc_u32 s11, s11, 0
	s_add_u32 s27, s27, 0x2000
	s_mov_b32 m0, s27
	v_lshl_add_u64 v[124:125], v[68:69], 0, s[10:11]
	global_load_lds_dwordx4 v[124:125], off
	s_add_u32 s10, s10, 0x2000
	s_addc_u32 s11, s11, 0
	s_add_u32 s27, s27, 0x2000
	s_mov_b32 m0, s27
	v_lshl_add_u64 v[124:125], v[68:69], 0, s[10:11]
	global_load_lds_dwordx4 v[124:125], off
	s_add_u32 s10, s10, 0x2000
	s_addc_u32 s11, s11, 0
	s_add_u32 s27, s27, 0x2000
	s_mov_b32 m0, s27
	v_lshl_add_u64 v[124:125], v[68:69], 0, s[10:11]
	global_load_lds_dwordx4 v[124:125], off
	s_waitcnt vmcnt(0)
.Lnm_fin_loop:
	s_waitcnt vmcnt(16)
	ds_read_b128 v[4:7], v136
	ds_read_b128 v[8:11], v136 offset:8192
	ds_read_b128 v[12:15], v136 offset:16384
	ds_read_b128 v[16:19], v136 offset:24576
	ds_read_b128 v[20:23], v136 offset:32768
	ds_read_b128 v[24:27], v136 offset:40960
	ds_read_b128 v[28:31], v136 offset:49152
	ds_read_b128 v[32:35], v136 offset:57344
	ds_read_b128 v[36:39], v137
	ds_read_b128 v[40:43], v137 offset:8192
	ds_read_b128 v[44:47], v137 offset:16384
	ds_read_b128 v[48:51], v137 offset:24576
	ds_read_b128 v[52:55], v137 offset:32768
	ds_read_b128 v[56:59], v137 offset:40960
	ds_read_b128 v[60:63], v137 offset:49152
	ds_read_b128 v[64:67], v137 offset:57344
	s_add_i32 s8, s4, -15
	s_ashr_i32 s9, s8, 31
	s_lshl_b64 s[24:25], s[8:9], 13
	s_add_i32 s28, s2, s34
	s_add_i32 s10, s8, s88
	s_cmpk_gt_i32 s28, 0x3ff
	s_cselect_b32 s10, s8, s10
	s_ashr_i32 s11, s10, 31
	s_lshl_b64 s[10:11], s[10:11], 13
	s_waitcnt lgkmcnt(0)
	s_lshl_b32 s27, s26, 10
	s_mov_b32 m0, s27
	v_lshl_add_u64 v[124:125], v[68:69], 0, s[10:11]
	global_load_lds_dwordx4 v[124:125], off
	s_add_u32 s10, s10, 0x2000
	s_addc_u32 s11, s11, 0
	s_add_u32 s27, s27, 0x2000
	s_mov_b32 m0, s27
	v_lshl_add_u64 v[124:125], v[68:69], 0, s[10:11]
	global_load_lds_dwordx4 v[124:125], off
	s_add_u32 s10, s10, 0x2000
	s_addc_u32 s11, s11, 0
	s_add_u32 s27, s27, 0x2000
	s_mov_b32 m0, s27
	v_lshl_add_u64 v[124:125], v[68:69], 0, s[10:11]
	global_load_lds_dwordx4 v[124:125], off
	s_add_u32 s10, s10, 0x2000
	s_addc_u32 s11, s11, 0
	s_add_u32 s27, s27, 0x2000
	s_mov_b32 m0, s27
	v_lshl_add_u64 v[124:125], v[68:69], 0, s[10:11]
	global_load_lds_dwordx4 v[124:125], off
	s_add_u32 s10, s10, 0x2000
	s_addc_u32 s11, s11, 0
	s_add_u32 s27, s27, 0x2000
	s_mov_b32 m0, s27
	v_lshl_add_u64 v[124:125], v[68:69], 0, s[10:11]
	global_load_lds_dwordx4 v[124:125], off
	s_add_u32 s10, s10, 0x2000
	s_addc_u32 s11, s11, 0
	s_add_u32 s27, s27, 0x2000
	s_mov_b32 m0, s27
	v_lshl_add_u64 v[124:125], v[68:69], 0, s[10:11]
	global_load_lds_dwordx4 v[124:125], off
	s_add_u32 s10, s10, 0x2000
	s_addc_u32 s11, s11, 0
	s_add_u32 s27, s27, 0x2000
	s_mov_b32 m0, s27
	v_lshl_add_u64 v[124:125], v[68:69], 0, s[10:11]
	global_load_lds_dwordx4 v[124:125], off
	s_add_u32 s10, s10, 0x2000
	s_addc_u32 s11, s11, 0
	s_add_u32 s27, s27, 0x2000
	s_mov_b32 m0, s27
	v_lshl_add_u64 v[124:125], v[68:69], 0, s[10:11]
	global_load_lds_dwordx4 v[124:125], off
	s_add_u32 s10, s10, 0x2000
	s_addc_u32 s11, s11, 0
	s_add_u32 s27, s27, 0x2000
	s_mov_b32 m0, s27
	v_lshl_add_u64 v[124:125], v[68:69], 0, s[10:11]
	global_load_lds_dwordx4 v[124:125], off
	s_add_u32 s10, s10, 0x2000
	s_addc_u32 s11, s11, 0
	s_add_u32 s27, s27, 0x2000
	s_mov_b32 m0, s27
	v_lshl_add_u64 v[124:125], v[68:69], 0, s[10:11]
	global_load_lds_dwordx4 v[124:125], off
	s_add_u32 s10, s10, 0x2000
	s_addc_u32 s11, s11, 0
	s_add_u32 s27, s27, 0x2000
	s_mov_b32 m0, s27
	v_lshl_add_u64 v[124:125], v[68:69], 0, s[10:11]
	global_load_lds_dwordx4 v[124:125], off
	s_add_u32 s10, s10, 0x2000
	s_addc_u32 s11, s11, 0
	s_add_u32 s27, s27, 0x2000
	s_mov_b32 m0, s27
	v_lshl_add_u64 v[124:125], v[68:69], 0, s[10:11]
	global_load_lds_dwordx4 v[124:125], off
	s_add_u32 s10, s10, 0x2000
	s_addc_u32 s11, s11, 0
	s_add_u32 s27, s27, 0x2000
	s_mov_b32 m0, s27
	v_lshl_add_u64 v[124:125], v[68:69], 0, s[10:11]
	global_load_lds_dwordx4 v[124:125], off
	s_add_u32 s10, s10, 0x2000
	s_addc_u32 s11, s11, 0
	s_add_u32 s27, s27, 0x2000
	s_mov_b32 m0, s27
	v_lshl_add_u64 v[124:125], v[68:69], 0, s[10:11]
	global_load_lds_dwordx4 v[124:125], off
	s_add_u32 s10, s10, 0x2000
	s_addc_u32 s11, s11, 0
	s_add_u32 s27, s27, 0x2000
	s_mov_b32 m0, s27
	v_lshl_add_u64 v[124:125], v[68:69], 0, s[10:11]
	global_load_lds_dwordx4 v[124:125], off
	s_add_u32 s10, s10, 0x2000
	s_addc_u32 s11, s11, 0
	s_add_u32 s27, s27, 0x2000
	s_mov_b32 m0, s27
	v_lshl_add_u64 v[124:125], v[68:69], 0, s[10:11]
	global_load_lds_dwordx4 v[124:125], off
	v_mul_f32_e32 v84, v5, v5
	v_mul_f32_e32 v100, v7, v7
	v_fmac_f32_e32 v84, v4, v4
	v_fmac_f32_e32 v100, v6, v6
	v_add_f32_e32 v84, v84, v100
	v_mul_f32_e32 v85, v9, v9
	v_mul_f32_e32 v101, v11, v11
	v_fmac_f32_e32 v85, v8, v8
	v_fmac_f32_e32 v101, v10, v10
	v_add_f32_e32 v85, v85, v101
	v_mul_f32_e32 v86, v13, v13
	v_mul_f32_e32 v102, v15, v15
	v_fmac_f32_e32 v86, v12, v12
	v_fmac_f32_e32 v102, v14, v14
	v_add_f32_e32 v86, v86, v102
	v_mul_f32_e32 v87, v17, v17
	v_mul_f32_e32 v103, v19, v19
	v_fmac_f32_e32 v87, v16, v16
	v_fmac_f32_e32 v103, v18, v18
	v_add_f32_e32 v87, v87, v103
	v_mul_f32_e32 v88, v21, v21
	v_mul_f32_e32 v104, v23, v23
	v_fmac_f32_e32 v88, v20, v20
	v_fmac_f32_e32 v104, v22, v22
	v_add_f32_e32 v88, v88, v104
	v_mul_f32_e32 v89, v25, v25
	v_mul_f32_e32 v105, v27, v27
	v_fmac_f32_e32 v89, v24, v24
	v_fmac_f32_e32 v105, v26, v26
	v_add_f32_e32 v89, v89, v105
	v_mul_f32_e32 v90, v29, v29
	v_mul_f32_e32 v106, v31, v31
	v_fmac_f32_e32 v90, v28, v28
	v_fmac_f32_e32 v106, v30, v30
	v_add_f32_e32 v90, v90, v106
	v_mul_f32_e32 v91, v33, v33
	v_mul_f32_e32 v107, v35, v35
	v_fmac_f32_e32 v91, v32, v32
	v_fmac_f32_e32 v107, v34, v34
	v_add_f32_e32 v91, v91, v107
	v_mul_f32_e32 v92, v37, v37
	v_mul_f32_e32 v108, v39, v39
	v_fmac_f32_e32 v92, v36, v36
	v_fmac_f32_e32 v108, v38, v38
	v_add_f32_e32 v92, v92, v108
	v_mul_f32_e32 v93, v41, v41
	v_mul_f32_e32 v109, v43, v43
	v_fmac_f32_e32 v93, v40, v40
	v_fmac_f32_e32 v109, v42, v42
	v_add_f32_e32 v93, v93, v109
	v_mul_f32_e32 v94, v45, v45
	v_mul_f32_e32 v110, v47, v47
	v_fmac_f32_e32 v94, v44, v44
	v_fmac_f32_e32 v110, v46, v46
	v_add_f32_e32 v94, v94, v110
	v_mul_f32_e32 v95, v49, v49
	v_mul_f32_e32 v111, v51, v51
	v_fmac_f32_e32 v95, v48, v48
	v_fmac_f32_e32 v111, v50, v50
	v_add_f32_e32 v95, v95, v111
	v_mul_f32_e32 v96, v53, v53
	v_mul_f32_e32 v112, v55, v55
	v_fmac_f32_e32 v96, v52, v52
	v_fmac_f32_e32 v112, v54, v54
	v_add_f32_e32 v96, v96, v112
	v_mul_f32_e32 v97, v57, v57
	v_mul_f32_e32 v113, v59, v59
	v_fmac_f32_e32 v97, v56, v56
	v_fmac_f32_e32 v113, v58, v58
	v_add_f32_e32 v97, v97, v113
	v_mul_f32_e32 v98, v61, v61
	v_mul_f32_e32 v114, v63, v63
	v_fmac_f32_e32 v98, v60, v60
	v_fmac_f32_e32 v114, v62, v62
	v_add_f32_e32 v98, v98, v114
	v_mul_f32_e32 v99, v65, v65
	v_mul_f32_e32 v115, v67, v67
	v_fmac_f32_e32 v99, v64, v64
	v_fmac_f32_e32 v115, v66, v66
	v_add_f32_e32 v99, v99, v115
	ds_bpermute_b32 v100, v73, v84
	ds_bpermute_b32 v101, v73, v85
	ds_bpermute_b32 v102, v73, v86
	ds_bpermute_b32 v103, v73, v87
	ds_bpermute_b32 v104, v73, v88
	ds_bpermute_b32 v105, v73, v89
	ds_bpermute_b32 v106, v73, v90
	ds_bpermute_b32 v107, v73, v91
	ds_bpermute_b32 v108, v73, v92
	ds_bpermute_b32 v109, v73, v93
	ds_bpermute_b32 v110, v73, v94
	ds_bpermute_b32 v111, v73, v95
	ds_bpermute_b32 v112, v73, v96
	ds_bpermute_b32 v113, v73, v97
	ds_bpermute_b32 v114, v73, v98
	ds_bpermute_b32 v115, v73, v99
	s_waitcnt lgkmcnt(15)
	v_add_f32_e32 v84, v84, v100
	s_waitcnt lgkmcnt(14)
	v_add_f32_e32 v85, v85, v101
	s_waitcnt lgkmcnt(13)
	v_add_f32_e32 v86, v86, v102
	s_waitcnt lgkmcnt(12)
	v_add_f32_e32 v87, v87, v103
	s_waitcnt lgkmcnt(11)
	v_add_f32_e32 v88, v88, v104
	s_waitcnt lgkmcnt(10)
	v_add_f32_e32 v89, v89, v105
	s_waitcnt lgkmcnt(9)
	v_add_f32_e32 v90, v90, v106
	s_waitcnt lgkmcnt(8)
	v_add_f32_e32 v91, v91, v107
	s_waitcnt lgkmcnt(7)
	v_add_f32_e32 v92, v92, v108
	s_waitcnt lgkmcnt(6)
	v_add_f32_e32 v93, v93, v109
	s_waitcnt lgkmcnt(5)
	v_add_f32_e32 v94, v94, v110
	s_waitcnt lgkmcnt(4)
	v_add_f32_e32 v95, v95, v111
	s_waitcnt lgkmcnt(3)
	v_add_f32_e32 v96, v96, v112
	s_waitcnt lgkmcnt(2)
	v_add_f32_e32 v97, v97, v113
	s_waitcnt lgkmcnt(1)
	v_add_f32_e32 v98, v98, v114
	s_waitcnt lgkmcnt(0)
	v_add_f32_e32 v99, v99, v115
	ds_bpermute_b32 v100, v74, v84
	ds_bpermute_b32 v101, v74, v85
	ds_bpermute_b32 v102, v74, v86
	ds_bpermute_b32 v103, v74, v87
	ds_bpermute_b32 v104, v74, v88
	ds_bpermute_b32 v105, v74, v89
	ds_bpermute_b32 v106, v74, v90
	ds_bpermute_b32 v107, v74, v91
	ds_bpermute_b32 v108, v74, v92
	ds_bpermute_b32 v109, v74, v93
	ds_bpermute_b32 v110, v74, v94
	ds_bpermute_b32 v111, v74, v95
	ds_bpermute_b32 v112, v74, v96
	ds_bpermute_b32 v113, v74, v97
	ds_bpermute_b32 v114, v74, v98
	ds_bpermute_b32 v115, v74, v99
	s_waitcnt lgkmcnt(15)
	v_add_f32_e32 v84, v84, v100
	s_waitcnt lgkmcnt(14)
	v_add_f32_e32 v85, v85, v101
	s_waitcnt lgkmcnt(13)
	v_add_f32_e32 v86, v86, v102
	s_waitcnt lgkmcnt(12)
	v_add_f32_e32 v87, v87, v103
	s_waitcnt lgkmcnt(11)
	v_add_f32_e32 v88, v88, v104
	s_waitcnt lgkmcnt(10)
	v_add_f32_e32 v89, v89, v105
	s_waitcnt lgkmcnt(9)
	v_add_f32_e32 v90, v90, v106
	s_waitcnt lgkmcnt(8)
	v_add_f32_e32 v91, v91, v107
	s_waitcnt lgkmcnt(7)
	v_add_f32_e32 v92, v92, v108
	s_waitcnt lgkmcnt(6)
	v_add_f32_e32 v93, v93, v109
	s_waitcnt lgkmcnt(5)
	v_add_f32_e32 v94, v94, v110
	s_waitcnt lgkmcnt(4)
	v_add_f32_e32 v95, v95, v111
	s_waitcnt lgkmcnt(3)
	v_add_f32_e32 v96, v96, v112
	s_waitcnt lgkmcnt(2)
	v_add_f32_e32 v97, v97, v113
	s_waitcnt lgkmcnt(1)
	v_add_f32_e32 v98, v98, v114
	s_waitcnt lgkmcnt(0)
	v_add_f32_e32 v99, v99, v115
	ds_bpermute_b32 v100, v75, v84
	ds_bpermute_b32 v101, v75, v85
	ds_bpermute_b32 v102, v75, v86
	ds_bpermute_b32 v103, v75, v87
	ds_bpermute_b32 v104, v75, v88
	ds_bpermute_b32 v105, v75, v89
	ds_bpermute_b32 v106, v75, v90
	ds_bpermute_b32 v107, v75, v91
	ds_bpermute_b32 v108, v75, v92
	ds_bpermute_b32 v109, v75, v93
	ds_bpermute_b32 v110, v75, v94
	ds_bpermute_b32 v111, v75, v95
	ds_bpermute_b32 v112, v75, v96
	ds_bpermute_b32 v113, v75, v97
	ds_bpermute_b32 v114, v75, v98
	ds_bpermute_b32 v115, v75, v99
	s_waitcnt lgkmcnt(15)
	v_add_f32_e32 v84, v84, v100
	s_waitcnt lgkmcnt(14)
	v_add_f32_e32 v85, v85, v101
	s_waitcnt lgkmcnt(13)
	v_add_f32_e32 v86, v86, v102
	s_waitcnt lgkmcnt(12)
	v_add_f32_e32 v87, v87, v103
	s_waitcnt lgkmcnt(11)
	v_add_f32_e32 v88, v88, v104
	s_waitcnt lgkmcnt(10)
	v_add_f32_e32 v89, v89, v105
	s_waitcnt lgkmcnt(9)
	v_add_f32_e32 v90, v90, v106
	s_waitcnt lgkmcnt(8)
	v_add_f32_e32 v91, v91, v107
	s_waitcnt lgkmcnt(7)
	v_add_f32_e32 v92, v92, v108
	s_waitcnt lgkmcnt(6)
	v_add_f32_e32 v93, v93, v109
	s_waitcnt lgkmcnt(5)
	v_add_f32_e32 v94, v94, v110
	s_waitcnt lgkmcnt(4)
	v_add_f32_e32 v95, v95, v111
	s_waitcnt lgkmcnt(3)
	v_add_f32_e32 v96, v96, v112
	s_waitcnt lgkmcnt(2)
	v_add_f32_e32 v97, v97, v113
	s_waitcnt lgkmcnt(1)
	v_add_f32_e32 v98, v98, v114
	s_waitcnt lgkmcnt(0)
	v_add_f32_e32 v99, v99, v115
	ds_bpermute_b32 v100, v76, v84
	ds_bpermute_b32 v101, v76, v85
	ds_bpermute_b32 v102, v76, v86
	ds_bpermute_b32 v103, v76, v87
	ds_bpermute_b32 v104, v76, v88
	ds_bpermute_b32 v105, v76, v89
	ds_bpermute_b32 v106, v76, v90
	ds_bpermute_b32 v107, v76, v91
	ds_bpermute_b32 v108, v76, v92
	ds_bpermute_b32 v109, v76, v93
	ds_bpermute_b32 v110, v76, v94
	ds_bpermute_b32 v111, v76, v95
	ds_bpermute_b32 v112, v76, v96
	ds_bpermute_b32 v113, v76, v97
	ds_bpermute_b32 v114, v76, v98
	ds_bpermute_b32 v115, v76, v99
	s_waitcnt lgkmcnt(15)
	v_add_f32_e32 v84, v84, v100
	s_waitcnt lgkmcnt(14)
	v_add_f32_e32 v85, v85, v101
	s_waitcnt lgkmcnt(13)
	v_add_f32_e32 v86, v86, v102
	s_waitcnt lgkmcnt(12)
	v_add_f32_e32 v87, v87, v103
	s_waitcnt lgkmcnt(11)
	v_add_f32_e32 v88, v88, v104
	s_waitcnt lgkmcnt(10)
	v_add_f32_e32 v89, v89, v105
	s_waitcnt lgkmcnt(9)
	v_add_f32_e32 v90, v90, v106
	s_waitcnt lgkmcnt(8)
	v_add_f32_e32 v91, v91, v107
	s_waitcnt lgkmcnt(7)
	v_add_f32_e32 v92, v92, v108
	s_waitcnt lgkmcnt(6)
	v_add_f32_e32 v93, v93, v109
	s_waitcnt lgkmcnt(5)
	v_add_f32_e32 v94, v94, v110
	s_waitcnt lgkmcnt(4)
	v_add_f32_e32 v95, v95, v111
	s_waitcnt lgkmcnt(3)
	v_add_f32_e32 v96, v96, v112
	s_waitcnt lgkmcnt(2)
	v_add_f32_e32 v97, v97, v113
	s_waitcnt lgkmcnt(1)
	v_add_f32_e32 v98, v98, v114
	s_waitcnt lgkmcnt(0)
	v_add_f32_e32 v99, v99, v115
	ds_bpermute_b32 v100, v77, v84
	ds_bpermute_b32 v101, v77, v85
	ds_bpermute_b32 v102, v77, v86
	ds_bpermute_b32 v103, v77, v87
	ds_bpermute_b32 v104, v77, v88
	ds_bpermute_b32 v105, v77, v89
	ds_bpermute_b32 v106, v77, v90
	ds_bpermute_b32 v107, v77, v91
	ds_bpermute_b32 v108, v77, v92
	ds_bpermute_b32 v109, v77, v93
	ds_bpermute_b32 v110, v77, v94
	ds_bpermute_b32 v111, v77, v95
	ds_bpermute_b32 v112, v77, v96
	ds_bpermute_b32 v113, v77, v97
	ds_bpermute_b32 v114, v77, v98
	ds_bpermute_b32 v115, v77, v99
	s_waitcnt lgkmcnt(15)
	v_add_f32_e32 v84, v84, v100
	s_waitcnt lgkmcnt(14)
	v_add_f32_e32 v85, v85, v101
	s_waitcnt lgkmcnt(13)
	v_add_f32_e32 v86, v86, v102
	s_waitcnt lgkmcnt(12)
	v_add_f32_e32 v87, v87, v103
	s_waitcnt lgkmcnt(11)
	v_add_f32_e32 v88, v88, v104
	s_waitcnt lgkmcnt(10)
	v_add_f32_e32 v89, v89, v105
	s_waitcnt lgkmcnt(9)
	v_add_f32_e32 v90, v90, v106
	s_waitcnt lgkmcnt(8)
	v_add_f32_e32 v91, v91, v107
	s_waitcnt lgkmcnt(7)
	v_add_f32_e32 v92, v92, v108
	s_waitcnt lgkmcnt(6)
	v_add_f32_e32 v93, v93, v109
	s_waitcnt lgkmcnt(5)
	v_add_f32_e32 v94, v94, v110
	s_waitcnt lgkmcnt(4)
	v_add_f32_e32 v95, v95, v111
	s_waitcnt lgkmcnt(3)
	v_add_f32_e32 v96, v96, v112
	s_waitcnt lgkmcnt(2)
	v_add_f32_e32 v97, v97, v113
	s_waitcnt lgkmcnt(1)
	v_add_f32_e32 v98, v98, v114
	s_waitcnt lgkmcnt(0)
	v_add_f32_e32 v99, v99, v115
	ds_bpermute_b32 v100, v78, v84
	ds_bpermute_b32 v101, v78, v85
	ds_bpermute_b32 v102, v78, v86
	ds_bpermute_b32 v103, v78, v87
	ds_bpermute_b32 v104, v78, v88
	ds_bpermute_b32 v105, v78, v89
	ds_bpermute_b32 v106, v78, v90
	ds_bpermute_b32 v107, v78, v91
	ds_bpermute_b32 v108, v78, v92
	ds_bpermute_b32 v109, v78, v93
	ds_bpermute_b32 v110, v78, v94
	ds_bpermute_b32 v111, v78, v95
	ds_bpermute_b32 v112, v78, v96
	ds_bpermute_b32 v113, v78, v97
	ds_bpermute_b32 v114, v78, v98
	ds_bpermute_b32 v115, v78, v99
	s_waitcnt lgkmcnt(15)
	v_add_f32_e32 v84, v84, v100
	s_waitcnt lgkmcnt(14)
	v_add_f32_e32 v85, v85, v101
	s_waitcnt lgkmcnt(13)
	v_add_f32_e32 v86, v86, v102
	s_waitcnt lgkmcnt(12)
	v_add_f32_e32 v87, v87, v103
	s_waitcnt lgkmcnt(11)
	v_add_f32_e32 v88, v88, v104
	s_waitcnt lgkmcnt(10)
	v_add_f32_e32 v89, v89, v105
	s_waitcnt lgkmcnt(9)
	v_add_f32_e32 v90, v90, v106
	s_waitcnt lgkmcnt(8)
	v_add_f32_e32 v91, v91, v107
	s_waitcnt lgkmcnt(7)
	v_add_f32_e32 v92, v92, v108
	s_waitcnt lgkmcnt(6)
	v_add_f32_e32 v93, v93, v109
	s_waitcnt lgkmcnt(5)
	v_add_f32_e32 v94, v94, v110
	s_waitcnt lgkmcnt(4)
	v_add_f32_e32 v95, v95, v111
	s_waitcnt lgkmcnt(3)
	v_add_f32_e32 v96, v96, v112
	s_waitcnt lgkmcnt(2)
	v_add_f32_e32 v97, v97, v113
	s_waitcnt lgkmcnt(1)
	v_add_f32_e32 v98, v98, v114
	s_waitcnt lgkmcnt(0)
	v_add_f32_e32 v99, v99, v115
	s_mov_b64 exec, 1
	ds_write_b128 v116, v[84:87]
	ds_write_b128 v116, v[88:91] offset:16
	ds_write_b128 v116, v[92:95] offset:32
	ds_write_b128 v116, v[96:99] offset:48
	s_mov_b64 exec, -1
	s_waitcnt lgkmcnt(0)
	s_barrier
	ds_read_b32 v128, v117
	ds_read_b32 v129, v117 offset:64
	ds_read_b32 v130, v117 offset:128
	ds_read_b32 v131, v117 offset:192
	ds_read_b32 v132, v117 offset:256
	ds_read_b32 v133, v117 offset:320
	ds_read_b32 v134, v117 offset:384
	ds_read_b32 v135, v117 offset:448
	s_waitcnt lgkmcnt(0)
	v_add_f32_e32 v128, v128, v129
	v_add_f32_e32 v130, v130, v131
	v_add_f32_e32 v132, v132, v133
	v_add_f32_e32 v134, v134, v135
	v_add_f32_e32 v128, v128, v130
	v_add_f32_e32 v132, v132, v134
	v_add_f32_e32 v128, v128, v132
	v_fmamk_f32 v128, v128, 0x3a000000, v79
	v_cmp_gt_f32_e32 vcc, s33, v128
	v_mul_f32_e32 v118, 0x4f800000, v128
	s_nop 1
	v_cndmask_b32_e32 v128, v128, v118, vcc
	v_sqrt_f32_e32 v118, v128
	s_nop 1
	v_add_u32_e32 v119, -1, v118
	v_fma_f32 v120, -v119, v118, v128
	v_cmp_ge_f32_e64 s[20:21], 0, v120
	v_add_u32_e32 v120, 1, v118
	s_nop 1
	v_cndmask_b32_e64 v119, v118, v119, s[20:21]
	v_fma_f32 v118, -v120, v118, v128
	v_cmp_lt_f32_e64 s[20:21], 0, v118
	s_nop 1
	v_cndmask_b32_e64 v118, v119, v120, s[20:21]
	v_mul_f32_e32 v119, 0x37800000, v118
	v_cndmask_b32_e32 v118, v118, v119, vcc
	v_cmp_class_f32_e32 vcc, v128, v80
	s_nop 1
	v_cndmask_b32_e32 v128, v118, v128, vcc
	v_div_scale_f32 v118, s[22:23], v128, v128, 1.0
	v_rcp_f32_e32 v119, v118
	s_nop 0
	v_fma_f32 v120, -v118, v119, 1.0
	v_fmac_f32_e32 v119, v120, v119
	v_div_scale_f32 v120, vcc, 1.0, v128, 1.0
	v_mul_f32_e32 v121, v120, v119
	v_fma_f32 v122, -v118, v121, v120
	v_fmac_f32_e32 v121, v122, v119
	v_fma_f32 v118, -v118, v121, v120
	v_div_fmas_f32 v118, v118, v119, v121
	v_div_fixup_f32 v118, v118, v128, 1.0
	v_readlane_b32 s12, v118, 0
	v_readlane_b32 s13, v118, 1
	v_readlane_b32 s14, v118, 2
	v_readlane_b32 s15, v118, 3
	v_readlane_b32 s16, v118, 4
	v_readlane_b32 s17, v118, 5
	v_readlane_b32 s18, v118, 6
	v_readlane_b32 s19, v118, 7
	s_nop 1
	v_mul_f32_e32 v4, s12, v4
	v_mul_f32_e32 v5, s12, v5
	v_mul_f32_e32 v6, s12, v6
	v_mul_f32_e32 v7, s12, v7
	v_pk_mul_f32 v[4:5], v[0:1], v[4:5]
	v_pk_mul_f32 v[6:7], v[2:3], v[6:7]
	v_lshl_add_u64 v[126:127], v[70:71], 0, s[24:25]
	global_store_dwordx4 v[126:127], v[4:7], off
	s_add_u32 s24, s24, 0x2000
	s_addc_u32 s25, s25, 0
	v_mul_f32_e32 v8, s13, v8
	v_mul_f32_e32 v9, s13, v9
	v_mul_f32_e32 v10, s13, v10
	v_mul_f32_e32 v11, s13, v11
	v_pk_mul_f32 v[8:9], v[0:1], v[8:9]
	v_pk_mul_f32 v[10:11], v[2:3], v[10:11]
	v_lshl_add_u64 v[126:127], v[70:71], 0, s[24:25]
	global_store_dwordx4 v[126:127], v[8:11], off
	s_add_u32 s24, s24, 0x2000
	s_addc_u32 s25, s25, 0
	v_mul_f32_e32 v12, s14, v12
	v_mul_f32_e32 v13, s14, v13
	v_mul_f32_e32 v14, s14, v14
	v_mul_f32_e32 v15, s14, v15
	v_pk_mul_f32 v[12:13], v[0:1], v[12:13]
	v_pk_mul_f32 v[14:15], v[2:3], v[14:15]
	v_lshl_add_u64 v[126:127], v[70:71], 0, s[24:25]
	global_store_dwordx4 v[126:127], v[12:15], off
	s_add_u32 s24, s24, 0x2000
	s_addc_u32 s25, s25, 0
	v_mul_f32_e32 v16, s15, v16
	v_mul_f32_e32 v17, s15, v17
	v_mul_f32_e32 v18, s15, v18
	v_mul_f32_e32 v19, s15, v19
	v_pk_mul_f32 v[16:17], v[0:1], v[16:17]
	v_pk_mul_f32 v[18:19], v[2:3], v[18:19]
	v_lshl_add_u64 v[126:127], v[70:71], 0, s[24:25]
	global_store_dwordx4 v[126:127], v[16:19], off
	s_add_u32 s24, s24, 0x2000
	s_addc_u32 s25, s25, 0
	v_mul_f32_e32 v20, s16, v20
	v_mul_f32_e32 v21, s16, v21
	v_mul_f32_e32 v22, s16, v22
	v_mul_f32_e32 v23, s16, v23
	v_pk_mul_f32 v[20:21], v[0:1], v[20:21]
	v_pk_mul_f32 v[22:23], v[2:3], v[22:23]
	v_lshl_add_u64 v[126:127], v[70:71], 0, s[24:25]
	global_store_dwordx4 v[126:127], v[20:23], off
	s_add_u32 s24, s24, 0x2000
	s_addc_u32 s25, s25, 0
	v_mul_f32_e32 v24, s17, v24
	v_mul_f32_e32 v25, s17, v25
	v_mul_f32_e32 v26, s17, v26
	v_mul_f32_e32 v27, s17, v27
	v_pk_mul_f32 v[24:25], v[0:1], v[24:25]
	v_pk_mul_f32 v[26:27], v[2:3], v[26:27]
	v_lshl_add_u64 v[126:127], v[70:71], 0, s[24:25]
	global_store_dwordx4 v[126:127], v[24:27], off
	s_add_u32 s24, s24, 0x2000
	s_addc_u32 s25, s25, 0
	v_mul_f32_e32 v28, s18, v28
	v_mul_f32_e32 v29, s18, v29
	v_mul_f32_e32 v30, s18, v30
	v_mul_f32_e32 v31, s18, v31
	v_pk_mul_f32 v[28:29], v[0:1], v[28:29]
	v_pk_mul_f32 v[30:31], v[2:3], v[30:31]
	v_lshl_add_u64 v[126:127], v[70:71], 0, s[24:25]
	global_store_dwordx4 v[126:127], v[28:31], off
	s_add_u32 s24, s24, 0x2000
	s_addc_u32 s25, s25, 0
	v_mul_f32_e32 v32, s19, v32
	v_mul_f32_e32 v33, s19, v33
	v_mul_f32_e32 v34, s19, v34
	v_mul_f32_e32 v35, s19, v35
	v_pk_mul_f32 v[32:33], v[0:1], v[32:33]
	v_pk_mul_f32 v[34:35], v[2:3], v[34:35]
	v_lshl_add_u64 v[126:127], v[70:71], 0, s[24:25]
	global_store_dwordx4 v[126:127], v[32:35], off
	s_add_u32 s24, s24, 0x2000
	s_addc_u32 s25, s25, 0
	v_readlane_b32 s12, v118, 8
	v_readlane_b32 s13, v118, 9
	v_readlane_b32 s14, v118, 10
	v_readlane_b32 s15, v118, 11
	v_readlane_b32 s16, v118, 12
	v_readlane_b32 s17, v118, 13
	v_readlane_b32 s18, v118, 14
	v_readlane_b32 s19, v118, 15
	s_nop 1
	v_mul_f32_e32 v36, s12, v36
	v_mul_f32_e32 v37, s12, v37
	v_mul_f32_e32 v38, s12, v38
	v_mul_f32_e32 v39, s12, v39
	v_pk_mul_f32 v[36:37], v[0:1], v[36:37]
	v_pk_mul_f32 v[38:39], v[2:3], v[38:39]
	v_lshl_add_u64 v[126:127], v[70:71], 0, s[24:25]
	global_store_dwordx4 v[126:127], v[36:39], off
	s_add_u32 s24, s24, 0x2000
	s_addc_u32 s25, s25, 0
	v_mul_f32_e32 v40, s13, v40
	v_mul_f32_e32 v41, s13, v41
	v_mul_f32_e32 v42, s13, v42
	v_mul_f32_e32 v43, s13, v43
	v_pk_mul_f32 v[40:41], v[0:1], v[40:41]
	v_pk_mul_f32 v[42:43], v[2:3], v[42:43]
	v_lshl_add_u64 v[126:127], v[70:71], 0, s[24:25]
	global_store_dwordx4 v[126:127], v[40:43], off
	s_add_u32 s24, s24, 0x2000
	s_addc_u32 s25, s25, 0
	v_mul_f32_e32 v44, s14, v44
	v_mul_f32_e32 v45, s14, v45
	v_mul_f32_e32 v46, s14, v46
	v_mul_f32_e32 v47, s14, v47
	v_pk_mul_f32 v[44:45], v[0:1], v[44:45]
	v_pk_mul_f32 v[46:47], v[2:3], v[46:47]
	v_lshl_add_u64 v[126:127], v[70:71], 0, s[24:25]
	global_store_dwordx4 v[126:127], v[44:47], off
	s_add_u32 s24, s24, 0x2000
	s_addc_u32 s25, s25, 0
	v_mul_f32_e32 v48, s15, v48
	v_mul_f32_e32 v49, s15, v49
	v_mul_f32_e32 v50, s15, v50
	v_mul_f32_e32 v51, s15, v51
	v_pk_mul_f32 v[48:49], v[0:1], v[48:49]
	v_pk_mul_f32 v[50:51], v[2:3], v[50:51]
	v_lshl_add_u64 v[126:127], v[70:71], 0, s[24:25]
	global_store_dwordx4 v[126:127], v[48:51], off
	s_add_u32 s24, s24, 0x2000
	s_addc_u32 s25, s25, 0
	v_mul_f32_e32 v52, s16, v52
	v_mul_f32_e32 v53, s16, v53
	v_mul_f32_e32 v54, s16, v54
	v_mul_f32_e32 v55, s16, v55
	v_pk_mul_f32 v[52:53], v[0:1], v[52:53]
	v_pk_mul_f32 v[54:55], v[2:3], v[54:55]
	v_lshl_add_u64 v[126:127], v[70:71], 0, s[24:25]
	global_store_dwordx4 v[126:127], v[52:55], off
	s_add_u32 s24, s24, 0x2000
	s_addc_u32 s25, s25, 0
	v_mul_f32_e32 v56, s17, v56
	v_mul_f32_e32 v57, s17, v57
	v_mul_f32_e32 v58, s17, v58
	v_mul_f32_e32 v59, s17, v59
	v_pk_mul_f32 v[56:57], v[0:1], v[56:57]
	v_pk_mul_f32 v[58:59], v[2:3], v[58:59]
	v_lshl_add_u64 v[126:127], v[70:71], 0, s[24:25]
	global_store_dwordx4 v[126:127], v[56:59], off
	s_add_u32 s24, s24, 0x2000
	s_addc_u32 s25, s25, 0
	v_mul_f32_e32 v60, s18, v60
	v_mul_f32_e32 v61, s18, v61
	v_mul_f32_e32 v62, s18, v62
	v_mul_f32_e32 v63, s18, v63
	v_pk_mul_f32 v[60:61], v[0:1], v[60:61]
	v_pk_mul_f32 v[62:63], v[2:3], v[62:63]
	v_lshl_add_u64 v[126:127], v[70:71], 0, s[24:25]
	global_store_dwordx4 v[126:127], v[60:63], off
	s_add_u32 s24, s24, 0x2000
	s_addc_u32 s25, s25, 0
	v_mul_f32_e32 v64, s19, v64
	v_mul_f32_e32 v65, s19, v65
	v_mul_f32_e32 v66, s19, v66
	v_mul_f32_e32 v67, s19, v67
	v_pk_mul_f32 v[64:65], v[0:1], v[64:65]
	v_pk_mul_f32 v[66:67], v[2:3], v[66:67]
	v_lshl_add_u64 v[126:127], v[70:71], 0, s[24:25]
	global_store_dwordx4 v[126:127], v[64:67], off
	s_add_u32 s24, s24, 0x2000
	s_addc_u32 s25, s25, 0
	s_waitcnt lgkmcnt(0)
	s_barrier
	s_add_i32 s2, s2, s34
	s_add_i32 s4, s4, s88
	s_cmpk_lt_i32 s2, 0x400
	s_cbranch_scc1 .Lnm_fin_loop
	s_waitcnt vmcnt(0)
	s_branch .LBB0_1382
